# gelu epilogue: select v<0?m:v-m rewritten as max(v,0)-|m| and |v|*c+1 via v_fma with abs modifier (bit-identical up to sign of zero); stale hazard nops removed
# speedup vs baseline: 1.0019x; 1.0019x over previous
.LBB0_173:
	v_fma_f32 v152, |v124|, s20, 1.0
	v_fma_f32 v153, |v125|, s20, 1.0
	v_pk_mul_f32 v[158:159], v[124:125], v[124:125]
	v_rcp_f32_e32 v154, v152
	v_rcp_f32_e32 v155, v153
	v_mov_b64_e32 v[152:153], s[24:25]
	v_pk_mul_f32 v[158:159], v[158:159], s[40:41] op_sel_hi:[1,0]
	v_pk_fma_f32 v[156:157], v[154:155], s[22:23], v[152:153] op_sel_hi:[1,0,0]
	v_pk_fma_f32 v[156:157], v[154:155], v[156:157], s[26:27] op_sel_hi:[1,1,0]
	v_exp_f32_e32 v158, v158
	v_exp_f32_e32 v159, v159
	v_fma_f32 v168, |v126|, s20, 1.0
	v_fma_f32 v169, |v127|, s20, 1.0
	v_pk_fma_f32 v[156:157], v[154:155], v[156:157], s[36:37] op_sel_hi:[1,1,0]
	v_rcp_f32_e32 v168, v168
	v_rcp_f32_e32 v169, v169
	v_pk_fma_f32 v[156:157], v[154:155], v[156:157], s[38:39] op_sel_hi:[1,1,0]
	v_pk_mul_f32 v[154:155], v[154:155], v[156:157]
	v_pk_mul_f32 v[156:157], v[126:127], v[126:127]
	v_pk_mul_f32 v[154:155], v[158:159], v[154:155]
	v_pk_mul_f32 v[156:157], v[156:157], s[40:41] op_sel_hi:[1,0]
	v_pk_mul_f32 v[158:159], v[124:125], v[154:155]
	v_max_f32_e32 v172, 0, v124
	v_max_f32_e32 v173, 0, v125
	v_pk_fma_f32 v[154:155], v[168:169], s[22:23], v[152:153] op_sel_hi:[1,0,0]
	v_exp_f32_e32 v156, v156
	v_pk_fma_f32 v[154:155], v[168:169], v[154:155], s[26:27] op_sel_hi:[1,1,0]
	v_exp_f32_e32 v157, v157
	v_pk_fma_f32 v[154:155], v[168:169], v[154:155], s[36:37] op_sel_hi:[1,1,0]
	v_pk_fma_f32 v[154:155], v[168:169], v[154:155], s[38:39] op_sel_hi:[1,1,0]
	v_fma_f32 v170, |v122|, s20, 1.0
	v_fma_f32 v171, |v123|, s20, 1.0
	v_pk_mul_f32 v[154:155], v[168:169], v[154:155]
	v_fma_f32 v168, |v120|, s20, 1.0
	v_fma_f32 v169, |v121|, s20, 1.0
	v_pk_mul_f32 v[154:155], v[156:157], v[154:155]
	v_rcp_f32_e32 v168, v168
	v_rcp_f32_e32 v169, v169
	v_pk_mul_f32 v[156:157], v[120:121], v[120:121]
	v_pk_mul_f32 v[174:175], v[126:127], v[154:155]
	v_max_f32_e32 v176, 0, v126
	v_max_f32_e32 v177, 0, v127
	v_pk_fma_f32 v[154:155], v[168:169], s[22:23], v[152:153] op_sel_hi:[1,0,0]
	v_pk_mul_f32 v[156:157], v[156:157], s[40:41] op_sel_hi:[1,0]
	v_pk_fma_f32 v[154:155], v[168:169], v[154:155], s[26:27] op_sel_hi:[1,1,0]
	v_exp_f32_e32 v156, v156
	v_exp_f32_e32 v157, v157
	v_pk_fma_f32 v[154:155], v[168:169], v[154:155], s[36:37] op_sel_hi:[1,1,0]
	v_rcp_f32_e32 v170, v170
	v_pk_fma_f32 v[154:155], v[168:169], v[154:155], s[38:39] op_sel_hi:[1,1,0]
	v_rcp_f32_e32 v171, v171
	v_pk_mul_f32 v[154:155], v[168:169], v[154:155]
	v_pk_mul_f32 v[154:155], v[156:157], v[154:155]
	v_pk_mul_f32 v[168:169], v[122:123], v[122:123]
	v_pk_mul_f32 v[156:157], v[120:121], v[154:155]
	v_max_f32_e32 v154, 0, v120
	v_max_f32_e32 v155, 0, v121
	v_pk_mul_f32 v[178:179], v[116:117], v[116:117]
	v_sub_f32_e64 v121, v155, |v157|
	v_pk_mul_f32 v[178:179], v[178:179], s[40:41] op_sel_hi:[1,0]
	v_sub_f32_e64 v120, v154, |v156|
	v_pk_fma_f32 v[154:155], v[170:171], s[22:23], v[152:153] op_sel_hi:[1,0,0]
	v_pk_mul_f32 v[156:157], v[168:169], s[40:41] op_sel_hi:[1,0]
	v_pk_fma_f32 v[154:155], v[170:171], v[154:155], s[26:27] op_sel_hi:[1,1,0]
	v_exp_f32_e32 v156, v156
	v_exp_f32_e32 v157, v157
	v_pk_fma_f32 v[154:155], v[170:171], v[154:155], s[36:37] op_sel_hi:[1,1,0]
	v_pk_fma_f32 v[154:155], v[170:171], v[154:155], s[38:39] op_sel_hi:[1,1,0]
	v_exp_f32_e32 v178, v178
	v_pk_mul_f32 v[154:155], v[170:171], v[154:155]
	v_exp_f32_e32 v179, v179
	v_pk_mul_f32 v[154:155], v[156:157], v[154:155]
	v_fma_f32 v180, |v118|, s20, 1.0
	v_fma_f32 v181, |v119|, s20, 1.0
	v_pk_mul_f32 v[168:169], v[122:123], v[154:155]
	v_max_f32_e32 v170, 0, v122
	v_max_f32_e32 v171, 0, v123
	v_fma_f32 v154, |v116|, s20, 1.0
	v_fma_f32 v155, |v117|, s20, 1.0
	v_rcp_f32_e32 v180, v180
	v_rcp_f32_e32 v154, v154
	v_rcp_f32_e32 v155, v155
	v_rcp_f32_e32 v181, v181
	s_cmp_gt_i32 s10, 11
	v_pk_fma_f32 v[156:157], v[154:155], s[22:23], v[152:153] op_sel_hi:[1,0,0]
	v_sub_f32_e64 v122, v170, |v168|
	v_pk_fma_f32 v[156:157], v[154:155], v[156:157], s[26:27] op_sel_hi:[1,1,0]
	v_pk_fma_f32 v[156:157], v[154:155], v[156:157], s[36:37] op_sel_hi:[1,1,0]
	v_lshl_add_u32 v148, s6, 8, v160
	v_pk_fma_f32 v[156:157], v[154:155], v[156:157], s[38:39] op_sel_hi:[1,1,0]
	s_cselect_b64 s[52:53], -1, 0
	v_pk_mul_f32 v[154:155], v[154:155], v[156:157]
	v_pk_mul_f32 v[156:157], v[118:119], v[118:119]
	v_pk_mul_f32 v[154:155], v[178:179], v[154:155]
	v_pk_mul_f32 v[156:157], v[156:157], s[40:41] op_sel_hi:[1,0]
	v_pk_mul_f32 v[178:179], v[116:117], v[154:155]
	v_max_f32_e32 v182, 0, v116
	v_max_f32_e32 v183, 0, v117
	v_pk_fma_f32 v[154:155], v[180:181], s[22:23], v[152:153] op_sel_hi:[1,0,0]
	v_exp_f32_e32 v156, v156
	v_pk_fma_f32 v[154:155], v[180:181], v[154:155], s[26:27] op_sel_hi:[1,1,0]
	v_exp_f32_e32 v157, v157
	v_pk_fma_f32 v[154:155], v[180:181], v[154:155], s[36:37] op_sel_hi:[1,1,0]
	s_lshl_b32 s33, s10, 1
	v_pk_fma_f32 v[154:155], v[180:181], v[154:155], s[38:39] op_sel_hi:[1,1,0]
	v_ashrrev_i32_e32 v149, 31, v148
	v_pk_mul_f32 v[154:155], v[180:181], v[154:155]
	v_mad_i64_i32 v[150:151], s[6:7], s33, v165, v[148:149]
	v_pk_mul_f32 v[154:155], v[156:157], v[154:155]
	v_lshlrev_b64 v[150:151], 8, v[150:151]
	v_pk_mul_f32 v[156:157], v[118:119], v[154:155]
	v_max_f32_e32 v180, 0, v118
	v_max_f32_e32 v181, 0, v119
	v_fma_f32 v154, |v112|, s20, 1.0
	v_fma_f32 v155, |v113|, s20, 1.0
	v_lshl_add_u64 v[150:151], v[138:139], 0, v[150:151]
	v_rcp_f32_e32 v184, v154
	v_rcp_f32_e32 v185, v155
	v_sub_f32_e64 v155, v180, |v156|
	v_cvt_pk_bf16_f32 v170, v120, v121
	s_cmp_lt_i32 s10, 12
	v_sub_f32_e64 v119, v181, |v157|
	v_pk_mul_f32 v[180:181], v[112:113], v[112:113]
	v_pk_fma_f32 v[156:157], v[184:185], s[22:23], v[152:153] op_sel_hi:[1,0,0]
	v_pk_mul_f32 v[180:181], v[180:181], s[40:41] op_sel_hi:[1,0]
	v_pk_fma_f32 v[156:157], v[184:185], v[156:157], s[26:27] op_sel_hi:[1,1,0]
	v_exp_f32_e32 v180, v180
	v_exp_f32_e32 v181, v181
	v_pk_fma_f32 v[156:157], v[184:185], v[156:157], s[36:37] op_sel_hi:[1,1,0]
	v_pk_fma_f32 v[156:157], v[184:185], v[156:157], s[38:39] op_sel_hi:[1,1,0]
	s_nop 0
	v_pk_mul_f32 v[156:157], v[184:185], v[156:157]
	v_pk_mul_f32 v[184:185], v[114:115], v[114:115]
	v_pk_mul_f32 v[156:157], v[180:181], v[156:157]
	s_nop 0
	v_pk_mul_f32 v[180:181], v[112:113], v[156:157]
	v_max_f32_e32 v186, 0, v112
	v_max_f32_e32 v187, 0, v113
	v_sub_f32_e64 v156, v172, |v158|
	v_sub_f32_e64 v157, v182, |v178|
	v_sub_f32_e64 v158, v173, |v159|
	v_fma_f32 v172, |v114|, s20, 1.0
	v_fma_f32 v173, |v115|, s20, 1.0
	v_sub_f32_e64 v124, v176, |v174|
	v_rcp_f32_e32 v172, v172
	v_rcp_f32_e32 v173, v173
	v_sub_f32_e64 v125, v183, |v179|
	v_cvt_pk_bf16_f32 v168, v156, v158
	v_pk_fma_f32 v[152:153], v[172:173], s[22:23], v[152:153] op_sel_hi:[1,0,0]
	v_sub_f32_e64 v126, v177, |v175|
	v_pk_fma_f32 v[152:153], v[172:173], v[152:153], s[26:27] op_sel_hi:[1,1,0]
	v_sub_f32_e64 v116, v186, |v180|
	v_pk_fma_f32 v[152:153], v[172:173], v[152:153], s[36:37] op_sel_hi:[1,1,0]
	v_sub_f32_e64 v117, v171, |v169|
	v_cvt_pk_bf16_f32 v169, v124, v126
	v_cvt_pk_bf16_f32 v171, v122, v117
	global_store_dwordx4 v[150:151], v[168:171], off
	v_pk_fma_f32 v[152:153], v[172:173], v[152:153], s[38:39] op_sel_hi:[1,1,0]
	s_nop 0
	v_pk_mul_f32 v[168:169], v[184:185], s[40:41] op_sel_hi:[1,0]
	v_pk_mul_f32 v[152:153], v[172:173], v[152:153]
	v_exp_f32_e32 v168, v168
	v_exp_f32_e32 v169, v169
	v_sub_f32_e64 v112, v187, |v181|
	v_cvt_pk_bf16_f32 v170, v116, v112
	v_pk_mul_f32 v[152:153], v[168:169], v[152:153]
	s_nop 0
	v_pk_mul_f32 v[168:169], v[114:115], v[152:153]
	v_max_f32_e32 v152, 0, v114
	v_max_f32_e32 v153, 0, v115
	v_sub_f32_e64 v115, v153, |v169|
	v_cvt_pk_bf16_f32 v169, v155, v119
	v_sub_f32_e64 v114, v152, |v168|
	v_add_co_u32_e32 v150, vcc, 0x820000, v150
	v_cvt_pk_bf16_f32 v168, v157, v125
	v_cvt_pk_bf16_f32 v171, v114, v115
	v_addc_co_u32_e32 v151, vcc, 0, v151, vcc
	global_store_dwordx4 v[150:151], v[168:171], off
	s_cbranch_scc1 .LBB0_177
	v_mov_b32_e32 v159, v157
	v_mov_b32_e32 v113, v117
	v_mov_b32_e32 v127, v125
	v_pk_add_f32 v[150:151], v[116:117], v[112:113]
	v_pk_mul_f32 v[152:153], v[116:117], v[112:113]
	v_mov_b32_e32 v168, v158
	v_pk_add_f32 v[172:173], v[156:157], v[158:159]
	v_pk_mul_f32 v[158:159], v[156:157], v[158:159]
	v_mov_b32_e32 v151, v153
	v_mov_b32_e32 v153, v124
	v_mov_b32_e32 v169, v126
	v_mov_b32_e32 v173, v159
	v_pk_add_f32 v[158:159], v[124:125], v[126:127]
	v_pk_mul_f32 v[126:127], v[124:125], v[126:127]
	v_and_b32_e32 v124, 64, v166
	v_xor_b32_e32 v123, 16, v166
	v_add_u32_e32 v124, 64, v124
	v_mov_b32_e32 v152, v156
	v_pk_mul_f32 v[168:169], v[168:169], v[168:169]
	v_mul_f32_e32 v118, v120, v120
	v_cmp_lt_i32_e32 vcc, v123, v124
	v_pk_fma_f32 v[152:153], v[152:153], v[152:153], v[168:169]
	v_pk_fma_f32 v[168:169], v[120:121], v[120:121], v[118:119] op_sel_hi:[1,1,0]
	v_mul_f32_e32 v118, v114, v114
	v_mov_b32_e32 v159, v127
	v_mul_f32_e32 v127, v155, v155
	v_mul_f32_e32 v175, v119, v119
	v_pk_mul_f32 v[176:177], v[116:117], v[116:117]
	v_pk_mul_f32 v[112:113], v[112:113], v[112:113]
	v_cndmask_b32_e32 v123, v166, v123, vcc
	v_mov_b32_e32 v126, v120
	v_mov_b32_e32 v174, v121
	v_pk_fma_f32 v[170:171], v[114:115], v[114:115], v[118:119] op_sel_hi:[1,1,0]
	v_mov_b32_e32 v154, v157
	v_mov_b32_e32 v118, v125
	v_lshlrev_b32_e32 v125, 2, v123
	v_mov_b32_e32 v123, v176
	v_pk_mov_b32 v[112:113], v[116:117], v[112:113] op_sel:[1,0]
	v_pk_add_f32 v[116:117], v[172:173], v[158:159]
	v_pk_add_f32 v[120:121], v[126:127], v[174:175]
	v_pk_add_f32 v[118:119], v[154:155], v[118:119]
	v_pk_add_f32 v[112:113], v[122:123], v[112:113]
	v_pk_add_f32 v[116:117], v[116:117], v[120:121]
	v_mul_f32_e32 v149, v122, v122
	v_pk_add_f32 v[152:153], v[152:153], v[152:153] op_sel_hi:[0,1]
	v_pk_add_f32 v[112:113], v[116:117], v[112:113]
	v_pk_add_f32 v[116:117], v[118:119], v[118:119] op_sel:[0,1] op_sel_hi:[1,0]
	v_mov_b32_e32 v152, v114
	v_mov_b32_e32 v168, v115
	v_mov_b32_e32 v117, v149
	v_mov_b32_e32 v137, v171
	v_pk_add_f32 v[114:115], v[152:153], v[168:169]
	v_pk_add_f32 v[116:117], v[116:117], v[150:151]
	v_pk_add_f32 v[112:113], v[112:113], v[136:137]
	v_pk_add_f32 v[114:115], v[116:117], v[114:115]
	v_xor_b32_e32 v116, 32, v166
	v_pk_add_f32 v[112:113], v[114:115], v[112:113]
	ds_bpermute_b32 v114, v125, v112
	ds_bpermute_b32 v115, v125, v113
	v_cmp_lt_i32_e32 vcc, v116, v124
	s_waitcnt lgkmcnt(0)
	v_pk_add_f32 v[112:113], v[112:113], v[114:115]
	v_cndmask_b32_e32 v116, v166, v116, vcc
	v_lshlrev_b32_e32 v116, 2, v116
	ds_bpermute_b32 v114, v116, v112
	ds_bpermute_b32 v115, v116, v113
	s_and_saveexec_b64 s[6:7], s[2:3]
	s_cbranch_execz .LBB0_176
	s_lshl_b32 s29, s10, 2
	s_sub_i32 s29, s29, 48
	s_waitcnt lgkmcnt(0)
	v_pk_add_f32 v[112:113], v[112:113], v[114:115]
	v_mov_b32_e32 v114, s29
	v_mov_b32_e32 v115, v136
	v_mad_i64_i32 v[114:115], s[34:35], v148, 48, v[114:115]
	v_or_b32_e32 v114, s61, v114
	v_lshl_add_u64 v[114:115], v[114:115], 3, s[14:15]
	global_store_dwordx2 v[114:115], v[112:113], off

.LBB0_177:
	v_fma_f32 v116, |v108|, s20, 1.0
	v_fma_f32 v117, |v109|, s20, 1.0
	v_pk_mul_f32 v[122:123], v[108:109], v[108:109]
	v_rcp_f32_e32 v118, v116
	v_rcp_f32_e32 v119, v117
	v_mov_b64_e32 v[116:117], s[24:25]
	v_pk_mul_f32 v[122:123], v[122:123], s[40:41] op_sel_hi:[1,0]
	v_pk_fma_f32 v[120:121], v[118:119], s[22:23], v[116:117] op_sel_hi:[1,0,0]
	v_pk_fma_f32 v[120:121], v[118:119], v[120:121], s[26:27] op_sel_hi:[1,1,0]
	v_exp_f32_e32 v122, v122
	v_exp_f32_e32 v123, v123
	v_fma_f32 v124, |v110|, s20, 1.0
	v_fma_f32 v125, |v111|, s20, 1.0
	v_pk_fma_f32 v[120:121], v[118:119], v[120:121], s[36:37] op_sel_hi:[1,1,0]
	v_rcp_f32_e32 v124, v124
	v_rcp_f32_e32 v125, v125
	v_pk_fma_f32 v[120:121], v[118:119], v[120:121], s[38:39] op_sel_hi:[1,1,0]
	v_pk_mul_f32 v[118:119], v[118:119], v[120:121]
	v_pk_mul_f32 v[120:121], v[110:111], v[110:111]
	v_pk_mul_f32 v[118:119], v[122:123], v[118:119]
	v_pk_mul_f32 v[120:121], v[120:121], s[40:41] op_sel_hi:[1,0]
	v_pk_mul_f32 v[122:123], v[108:109], v[118:119]
	v_max_f32_e32 v150, 0, v108
	v_max_f32_e32 v151, 0, v109
	v_pk_fma_f32 v[118:119], v[124:125], s[22:23], v[116:117] op_sel_hi:[1,0,0]
	v_exp_f32_e32 v120, v120
	v_pk_fma_f32 v[118:119], v[124:125], v[118:119], s[26:27] op_sel_hi:[1,1,0]
	v_exp_f32_e32 v121, v121
	v_pk_fma_f32 v[118:119], v[124:125], v[118:119], s[36:37] op_sel_hi:[1,1,0]
	v_pk_fma_f32 v[118:119], v[124:125], v[118:119], s[38:39] op_sel_hi:[1,1,0]
	v_fma_f32 v126, |v106|, s20, 1.0
	v_fma_f32 v127, |v107|, s20, 1.0
	v_pk_mul_f32 v[118:119], v[124:125], v[118:119]
	v_fma_f32 v124, |v104|, s20, 1.0
	v_fma_f32 v125, |v105|, s20, 1.0
	v_pk_mul_f32 v[118:119], v[120:121], v[118:119]
	v_rcp_f32_e32 v124, v124
	v_rcp_f32_e32 v125, v125
	v_pk_mul_f32 v[120:121], v[104:105], v[104:105]
	v_pk_mul_f32 v[152:153], v[110:111], v[118:119]
	v_max_f32_e32 v154, 0, v110
	v_max_f32_e32 v155, 0, v111
	v_pk_fma_f32 v[118:119], v[124:125], s[22:23], v[116:117] op_sel_hi:[1,0,0]
	v_pk_mul_f32 v[120:121], v[120:121], s[40:41] op_sel_hi:[1,0]
	v_pk_fma_f32 v[118:119], v[124:125], v[118:119], s[26:27] op_sel_hi:[1,1,0]
	v_exp_f32_e32 v120, v120
	v_exp_f32_e32 v121, v121
	v_pk_fma_f32 v[118:119], v[124:125], v[118:119], s[36:37] op_sel_hi:[1,1,0]
	v_rcp_f32_e32 v126, v126
	v_pk_fma_f32 v[118:119], v[124:125], v[118:119], s[38:39] op_sel_hi:[1,1,0]
	v_rcp_f32_e32 v127, v127
	v_pk_mul_f32 v[118:119], v[124:125], v[118:119]
	v_pk_mul_f32 v[118:119], v[120:121], v[118:119]
	v_pk_mul_f32 v[124:125], v[106:107], v[106:107]
	v_pk_mul_f32 v[120:121], v[104:105], v[118:119]
	v_max_f32_e32 v118, 0, v104
	v_max_f32_e32 v119, 0, v105
	v_pk_mul_f32 v[156:157], v[100:101], v[100:101]
	v_sub_f32_e64 v105, v119, |v121|
	v_pk_mul_f32 v[156:157], v[156:157], s[40:41] op_sel_hi:[1,0]
	v_sub_f32_e64 v104, v118, |v120|
	v_pk_fma_f32 v[118:119], v[126:127], s[22:23], v[116:117] op_sel_hi:[1,0,0]
	v_pk_mul_f32 v[120:121], v[124:125], s[40:41] op_sel_hi:[1,0]
	v_pk_fma_f32 v[118:119], v[126:127], v[118:119], s[26:27] op_sel_hi:[1,1,0]
	v_exp_f32_e32 v120, v120
	v_exp_f32_e32 v121, v121
	v_pk_fma_f32 v[118:119], v[126:127], v[118:119], s[36:37] op_sel_hi:[1,1,0]
	v_pk_fma_f32 v[118:119], v[126:127], v[118:119], s[38:39] op_sel_hi:[1,1,0]
	v_exp_f32_e32 v156, v156
	v_pk_mul_f32 v[118:119], v[126:127], v[118:119]
	v_exp_f32_e32 v157, v157
	v_pk_mul_f32 v[118:119], v[120:121], v[118:119]
	v_fma_f32 v158, |v102|, s20, 1.0
	v_fma_f32 v159, |v103|, s20, 1.0
	v_pk_mul_f32 v[124:125], v[106:107], v[118:119]
	v_max_f32_e32 v126, 0, v106
	v_max_f32_e32 v127, 0, v107
	v_fma_f32 v118, |v100|, s20, 1.0
	v_fma_f32 v119, |v101|, s20, 1.0
	v_rcp_f32_e32 v158, v158
	v_rcp_f32_e32 v118, v118
	v_rcp_f32_e32 v119, v119
	v_rcp_f32_e32 v159, v159
	v_or_b32_e32 v112, 16, v148
	v_pk_fma_f32 v[120:121], v[118:119], s[22:23], v[116:117] op_sel_hi:[1,0,0]
	v_sub_f32_e64 v106, v126, |v124|
	v_pk_fma_f32 v[120:121], v[118:119], v[120:121], s[26:27] op_sel_hi:[1,1,0]
	v_pk_fma_f32 v[120:121], v[118:119], v[120:121], s[36:37] op_sel_hi:[1,1,0]
	s_mul_i32 s50, s10, 0x10400
	v_pk_fma_f32 v[120:121], v[118:119], v[120:121], s[38:39] op_sel_hi:[1,1,0]
	s_mul_hi_i32 s51, s33, 0x8200
	v_pk_mul_f32 v[118:119], v[118:119], v[120:121]
	v_pk_mul_f32 v[120:121], v[102:103], v[102:103]
	v_pk_mul_f32 v[118:119], v[156:157], v[118:119]
	v_pk_mul_f32 v[120:121], v[120:121], s[40:41] op_sel_hi:[1,0]
	v_pk_mul_f32 v[156:157], v[100:101], v[118:119]
	v_max_f32_e32 v168, 0, v100
	v_max_f32_e32 v169, 0, v101
	v_pk_fma_f32 v[118:119], v[158:159], s[22:23], v[116:117] op_sel_hi:[1,0,0]
	v_exp_f32_e32 v120, v120
	v_pk_fma_f32 v[118:119], v[158:159], v[118:119], s[26:27] op_sel_hi:[1,1,0]
	v_exp_f32_e32 v121, v121
	v_pk_fma_f32 v[118:119], v[158:159], v[118:119], s[36:37] op_sel_hi:[1,1,0]
	v_ashrrev_i32_e32 v113, 31, v112
	v_pk_fma_f32 v[118:119], v[158:159], v[118:119], s[38:39] op_sel_hi:[1,1,0]
	s_waitcnt lgkmcnt(0)
	v_lshl_add_u64 v[114:115], s[50:51], 0, v[112:113]
	v_pk_mul_f32 v[118:119], v[158:159], v[118:119]
	v_lshlrev_b64 v[114:115], 8, v[114:115]
	v_pk_mul_f32 v[118:119], v[120:121], v[118:119]
	v_lshl_add_u64 v[114:115], v[138:139], 0, v[114:115]
	v_pk_mul_f32 v[120:121], v[102:103], v[118:119]
	v_max_f32_e32 v158, 0, v102
	v_max_f32_e32 v159, 0, v103
	v_fma_f32 v118, |v96|, s20, 1.0
	v_fma_f32 v119, |v97|, s20, 1.0
	v_cvt_pk_bf16_f32 v126, v104, v105
	v_rcp_f32_e32 v170, v118
	v_rcp_f32_e32 v171, v119
	v_sub_f32_e64 v119, v158, |v120|
	v_cndmask_b32_e64 v102, 0, 1, s[52:53]
	v_cmp_ne_u32_e64 s[6:7], 1, v102
	v_sub_f32_e64 v103, v159, |v121|
	v_pk_mul_f32 v[158:159], v[96:97], v[96:97]
	v_pk_fma_f32 v[120:121], v[170:171], s[22:23], v[116:117] op_sel_hi:[1,0,0]
	v_pk_mul_f32 v[158:159], v[158:159], s[40:41] op_sel_hi:[1,0]
	v_pk_fma_f32 v[120:121], v[170:171], v[120:121], s[26:27] op_sel_hi:[1,1,0]
	v_exp_f32_e32 v158, v158
	v_exp_f32_e32 v159, v159
	v_pk_fma_f32 v[120:121], v[170:171], v[120:121], s[36:37] op_sel_hi:[1,1,0]
	v_pk_fma_f32 v[120:121], v[170:171], v[120:121], s[38:39] op_sel_hi:[1,1,0]
	s_nop 0
	v_pk_mul_f32 v[120:121], v[170:171], v[120:121]
	v_pk_mul_f32 v[170:171], v[98:99], v[98:99]
	v_pk_mul_f32 v[120:121], v[158:159], v[120:121]
	s_nop 0
	v_pk_mul_f32 v[158:159], v[96:97], v[120:121]
	v_max_f32_e32 v172, 0, v96
	v_max_f32_e32 v173, 0, v97
	v_sub_f32_e64 v120, v150, |v122|
	v_sub_f32_e64 v121, v168, |v156|
	v_sub_f32_e64 v122, v151, |v123|
	v_fma_f32 v150, |v98|, s20, 1.0
	v_fma_f32 v151, |v99|, s20, 1.0
	v_sub_f32_e64 v108, v154, |v152|
	v_rcp_f32_e32 v150, v150
	v_rcp_f32_e32 v151, v151
	v_sub_f32_e64 v109, v169, |v157|
	v_cvt_pk_bf16_f32 v124, v120, v122
	v_pk_fma_f32 v[116:117], v[150:151], s[22:23], v[116:117] op_sel_hi:[1,0,0]
	v_sub_f32_e64 v110, v155, |v153|
	v_pk_fma_f32 v[116:117], v[150:151], v[116:117], s[26:27] op_sel_hi:[1,1,0]
	v_sub_f32_e64 v100, v172, |v158|
	v_pk_fma_f32 v[116:117], v[150:151], v[116:117], s[36:37] op_sel_hi:[1,1,0]
	v_sub_f32_e64 v101, v127, |v125|
	v_cvt_pk_bf16_f32 v125, v108, v110
	v_cvt_pk_bf16_f32 v127, v106, v101
	global_store_dwordx4 v[114:115], v[124:127], off
	v_pk_fma_f32 v[116:117], v[150:151], v[116:117], s[38:39] op_sel_hi:[1,1,0]
	s_nop 0
	v_pk_mul_f32 v[124:125], v[170:171], s[40:41] op_sel_hi:[1,0]
	v_pk_mul_f32 v[116:117], v[150:151], v[116:117]
	v_exp_f32_e32 v124, v124
	v_exp_f32_e32 v125, v125
	v_sub_f32_e64 v96, v173, |v159|
	v_cvt_pk_bf16_f32 v126, v100, v96
	v_pk_mul_f32 v[116:117], v[124:125], v[116:117]
	s_nop 0
	v_pk_mul_f32 v[124:125], v[98:99], v[116:117]
	v_max_f32_e32 v116, 0, v98
	v_max_f32_e32 v117, 0, v99
	v_sub_f32_e64 v99, v117, |v125|
	v_cvt_pk_bf16_f32 v125, v119, v103
	v_sub_f32_e64 v98, v116, |v124|
	v_add_co_u32_e32 v114, vcc, 0x820000, v114
	v_cvt_pk_bf16_f32 v124, v121, v109
	s_nop 0
	v_addc_co_u32_e32 v115, vcc, 0, v115, vcc
	v_cvt_pk_bf16_f32 v127, v98, v99
	s_andn2_b64 vcc, exec, s[52:53]
	global_store_dwordx4 v[114:115], v[124:127], off
	s_cbranch_vccnz .LBB0_181
	v_mov_b32_e32 v123, v121
	v_mov_b32_e32 v97, v101
	v_mov_b32_e32 v111, v109
	v_pk_add_f32 v[114:115], v[100:101], v[96:97]
	v_pk_mul_f32 v[116:117], v[100:101], v[96:97]
	v_mov_b32_e32 v124, v122
	v_pk_add_f32 v[150:151], v[120:121], v[122:123]
	v_pk_mul_f32 v[122:123], v[120:121], v[122:123]
	v_mov_b32_e32 v115, v117
	v_mov_b32_e32 v117, v108
	v_mov_b32_e32 v125, v110
	v_mov_b32_e32 v151, v123
	v_pk_add_f32 v[122:123], v[108:109], v[110:111]
	v_pk_mul_f32 v[110:111], v[108:109], v[110:111]
	v_and_b32_e32 v108, 64, v166
	v_xor_b32_e32 v107, 16, v166
	v_add_u32_e32 v108, 64, v108
	v_mov_b32_e32 v116, v120
	v_pk_mul_f32 v[124:125], v[124:125], v[124:125]
	v_mul_f32_e32 v102, v104, v104
	v_cmp_lt_i32_e32 vcc, v107, v108
	v_pk_fma_f32 v[116:117], v[116:117], v[116:117], v[124:125]
	v_pk_fma_f32 v[124:125], v[104:105], v[104:105], v[102:103] op_sel_hi:[1,1,0]
	v_mul_f32_e32 v102, v98, v98
	v_mov_b32_e32 v123, v111
	v_mul_f32_e32 v111, v119, v119
	v_mul_f32_e32 v153, v103, v103
	v_pk_mul_f32 v[154:155], v[100:101], v[100:101]
	v_pk_mul_f32 v[96:97], v[96:97], v[96:97]
	v_cndmask_b32_e32 v107, v166, v107, vcc
	v_mov_b32_e32 v110, v104
	v_mov_b32_e32 v152, v105
	v_pk_fma_f32 v[126:127], v[98:99], v[98:99], v[102:103] op_sel_hi:[1,1,0]
	v_mov_b32_e32 v118, v121
	v_mov_b32_e32 v102, v109
	v_lshlrev_b32_e32 v109, 2, v107
	v_mov_b32_e32 v107, v154
	v_pk_mov_b32 v[96:97], v[100:101], v[96:97] op_sel:[1,0]
	v_pk_add_f32 v[100:101], v[150:151], v[122:123]
	v_pk_add_f32 v[104:105], v[110:111], v[152:153]
	v_pk_add_f32 v[102:103], v[118:119], v[102:103]
	v_pk_add_f32 v[96:97], v[106:107], v[96:97]
	v_pk_add_f32 v[100:101], v[100:101], v[104:105]
	v_mul_f32_e32 v113, v106, v106
	v_pk_add_f32 v[116:117], v[116:117], v[116:117] op_sel_hi:[0,1]
	v_pk_add_f32 v[96:97], v[100:101], v[96:97]
	v_pk_add_f32 v[100:101], v[102:103], v[102:103] op_sel:[0,1] op_sel_hi:[1,0]
	v_mov_b32_e32 v116, v98
	v_mov_b32_e32 v124, v99
	v_mov_b32_e32 v101, v113
	v_mov_b32_e32 v137, v127
	v_pk_add_f32 v[98:99], v[116:117], v[124:125]
	v_pk_add_f32 v[100:101], v[100:101], v[114:115]
	v_pk_add_f32 v[96:97], v[96:97], v[136:137]
	v_pk_add_f32 v[98:99], v[100:101], v[98:99]
	v_xor_b32_e32 v100, 32, v166
	v_pk_add_f32 v[96:97], v[98:99], v[96:97]
	ds_bpermute_b32 v98, v109, v96
	ds_bpermute_b32 v99, v109, v97
	v_cmp_lt_i32_e32 vcc, v100, v108
	s_waitcnt lgkmcnt(0)
	v_pk_add_f32 v[96:97], v[96:97], v[98:99]
	v_cndmask_b32_e32 v100, v166, v100, vcc
	v_lshlrev_b32_e32 v100, 2, v100
	ds_bpermute_b32 v98, v100, v96
	ds_bpermute_b32 v99, v100, v97
	s_and_saveexec_b64 s[52:53], s[2:3]
	s_cbranch_execz .LBB0_180
	s_lshl_b32 s29, s10, 2
	s_sub_i32 s29, s29, 48
	s_waitcnt lgkmcnt(0)
	v_pk_add_f32 v[96:97], v[96:97], v[98:99]
	v_mov_b32_e32 v98, s29
	v_mov_b32_e32 v99, v136
	v_mad_i64_i32 v[98:99], s[34:35], v112, 48, v[98:99]
	v_or_b32_e32 v98, s61, v98
	v_lshl_add_u64 v[98:99], v[98:99], 3, s[14:15]
	global_store_dwordx2 v[98:99], v[96:97], off

.LBB0_181:
	v_fma_f32 v100, |v92|, s20, 1.0
	v_fma_f32 v101, |v93|, s20, 1.0
	v_pk_mul_f32 v[106:107], v[92:93], v[92:93]
	v_rcp_f32_e32 v102, v100
	v_rcp_f32_e32 v103, v101
	v_mov_b64_e32 v[100:101], s[24:25]
	v_pk_mul_f32 v[106:107], v[106:107], s[40:41] op_sel_hi:[1,0]
	v_pk_fma_f32 v[104:105], v[102:103], s[22:23], v[100:101] op_sel_hi:[1,0,0]
	v_pk_fma_f32 v[104:105], v[102:103], v[104:105], s[26:27] op_sel_hi:[1,1,0]
	v_exp_f32_e32 v106, v106
	v_exp_f32_e32 v107, v107
	v_fma_f32 v108, |v94|, s20, 1.0
	v_fma_f32 v109, |v95|, s20, 1.0
	v_pk_fma_f32 v[104:105], v[102:103], v[104:105], s[36:37] op_sel_hi:[1,1,0]
	v_rcp_f32_e32 v108, v108
	v_rcp_f32_e32 v109, v109
	v_pk_fma_f32 v[104:105], v[102:103], v[104:105], s[38:39] op_sel_hi:[1,1,0]
	v_pk_mul_f32 v[102:103], v[102:103], v[104:105]
	v_pk_mul_f32 v[104:105], v[94:95], v[94:95]
	v_pk_mul_f32 v[102:103], v[106:107], v[102:103]
	v_pk_mul_f32 v[104:105], v[104:105], s[40:41] op_sel_hi:[1,0]
	v_pk_mul_f32 v[106:107], v[92:93], v[102:103]
	v_max_f32_e32 v112, 0, v92
	v_max_f32_e32 v113, 0, v93
	v_pk_fma_f32 v[102:103], v[108:109], s[22:23], v[100:101] op_sel_hi:[1,0,0]
	v_exp_f32_e32 v104, v104
	v_pk_fma_f32 v[102:103], v[108:109], v[102:103], s[26:27] op_sel_hi:[1,1,0]
	v_exp_f32_e32 v105, v105
	v_pk_fma_f32 v[102:103], v[108:109], v[102:103], s[36:37] op_sel_hi:[1,1,0]
	v_pk_fma_f32 v[102:103], v[108:109], v[102:103], s[38:39] op_sel_hi:[1,1,0]
	v_fma_f32 v110, |v90|, s20, 1.0
	v_fma_f32 v111, |v91|, s20, 1.0
	v_pk_mul_f32 v[102:103], v[108:109], v[102:103]
	v_fma_f32 v108, |v88|, s20, 1.0
	v_fma_f32 v109, |v89|, s20, 1.0
	v_pk_mul_f32 v[102:103], v[104:105], v[102:103]
	v_rcp_f32_e32 v108, v108
	v_rcp_f32_e32 v109, v109
	v_pk_mul_f32 v[104:105], v[88:89], v[88:89]
	v_pk_mul_f32 v[114:115], v[94:95], v[102:103]
	v_max_f32_e32 v116, 0, v94
	v_max_f32_e32 v117, 0, v95
	v_pk_fma_f32 v[102:103], v[108:109], s[22:23], v[100:101] op_sel_hi:[1,0,0]
	v_pk_mul_f32 v[104:105], v[104:105], s[40:41] op_sel_hi:[1,0]
	v_pk_fma_f32 v[102:103], v[108:109], v[102:103], s[26:27] op_sel_hi:[1,1,0]
	v_exp_f32_e32 v104, v104
	v_exp_f32_e32 v105, v105
	v_pk_fma_f32 v[102:103], v[108:109], v[102:103], s[36:37] op_sel_hi:[1,1,0]
	v_rcp_f32_e32 v110, v110
	v_pk_fma_f32 v[102:103], v[108:109], v[102:103], s[38:39] op_sel_hi:[1,1,0]
	v_rcp_f32_e32 v111, v111
	v_pk_mul_f32 v[102:103], v[108:109], v[102:103]
	v_pk_mul_f32 v[102:103], v[104:105], v[102:103]
	v_pk_mul_f32 v[108:109], v[90:91], v[90:91]
	v_pk_mul_f32 v[104:105], v[88:89], v[102:103]
	v_max_f32_e32 v102, 0, v88
	v_max_f32_e32 v103, 0, v89
	v_pk_mul_f32 v[118:119], v[84:85], v[84:85]
	v_sub_f32_e64 v89, v103, |v105|
	v_pk_mul_f32 v[118:119], v[118:119], s[40:41] op_sel_hi:[1,0]
	v_sub_f32_e64 v88, v102, |v104|
	v_pk_fma_f32 v[102:103], v[110:111], s[22:23], v[100:101] op_sel_hi:[1,0,0]
	v_pk_mul_f32 v[104:105], v[108:109], s[40:41] op_sel_hi:[1,0]
	v_pk_fma_f32 v[102:103], v[110:111], v[102:103], s[26:27] op_sel_hi:[1,1,0]
	v_exp_f32_e32 v104, v104
	v_exp_f32_e32 v105, v105
	v_pk_fma_f32 v[102:103], v[110:111], v[102:103], s[36:37] op_sel_hi:[1,1,0]
	v_pk_fma_f32 v[102:103], v[110:111], v[102:103], s[38:39] op_sel_hi:[1,1,0]
	v_exp_f32_e32 v118, v118
	v_pk_mul_f32 v[102:103], v[110:111], v[102:103]
	v_exp_f32_e32 v119, v119
	v_pk_mul_f32 v[102:103], v[104:105], v[102:103]
	v_fma_f32 v120, |v86|, s20, 1.0
	v_fma_f32 v121, |v87|, s20, 1.0
	v_pk_mul_f32 v[108:109], v[90:91], v[102:103]
	v_max_f32_e32 v110, 0, v90
	v_max_f32_e32 v111, 0, v91
	v_fma_f32 v102, |v84|, s20, 1.0
	v_fma_f32 v103, |v85|, s20, 1.0
	v_rcp_f32_e32 v120, v120
	v_rcp_f32_e32 v102, v102
	v_rcp_f32_e32 v103, v103
	v_rcp_f32_e32 v121, v121
	v_or_b32_e32 v96, 32, v148
	v_pk_fma_f32 v[104:105], v[102:103], s[22:23], v[100:101] op_sel_hi:[1,0,0]
	v_sub_f32_e64 v90, v110, |v108|
	v_pk_fma_f32 v[104:105], v[102:103], v[104:105], s[26:27] op_sel_hi:[1,1,0]
	v_pk_fma_f32 v[104:105], v[102:103], v[104:105], s[36:37] op_sel_hi:[1,1,0]
	v_ashrrev_i32_e32 v97, 31, v96
	v_pk_fma_f32 v[104:105], v[102:103], v[104:105], s[38:39] op_sel_hi:[1,1,0]
	s_waitcnt lgkmcnt(0)
	v_lshl_add_u64 v[98:99], s[50:51], 0, v[96:97]
	v_pk_mul_f32 v[102:103], v[102:103], v[104:105]
	v_pk_mul_f32 v[104:105], v[86:87], v[86:87]
	v_pk_mul_f32 v[102:103], v[118:119], v[102:103]
	v_pk_mul_f32 v[104:105], v[104:105], s[40:41] op_sel_hi:[1,0]
	v_pk_mul_f32 v[118:119], v[84:85], v[102:103]
	v_max_f32_e32 v122, 0, v84
	v_max_f32_e32 v123, 0, v85
	v_pk_fma_f32 v[102:103], v[120:121], s[22:23], v[100:101] op_sel_hi:[1,0,0]
	v_exp_f32_e32 v104, v104
	v_pk_fma_f32 v[102:103], v[120:121], v[102:103], s[26:27] op_sel_hi:[1,1,0]
	v_exp_f32_e32 v105, v105
	v_pk_fma_f32 v[102:103], v[120:121], v[102:103], s[36:37] op_sel_hi:[1,1,0]
	v_lshlrev_b64 v[98:99], 8, v[98:99]
	v_pk_fma_f32 v[102:103], v[120:121], v[102:103], s[38:39] op_sel_hi:[1,1,0]
	v_lshl_add_u64 v[98:99], v[138:139], 0, v[98:99]
	v_pk_mul_f32 v[102:103], v[120:121], v[102:103]
	v_cvt_pk_bf16_f32 v110, v88, v89
	v_pk_mul_f32 v[102:103], v[104:105], v[102:103]
	s_nop 0
	v_pk_mul_f32 v[104:105], v[86:87], v[102:103]
	v_max_f32_e32 v120, 0, v86
	v_max_f32_e32 v121, 0, v87
	v_fma_f32 v102, |v80|, s20, 1.0
	v_fma_f32 v103, |v81|, s20, 1.0
	s_nop 0
	v_rcp_f32_e32 v124, v102
	v_rcp_f32_e32 v125, v103
	v_sub_f32_e64 v103, v120, |v104|
	v_sub_f32_e64 v87, v121, |v105|
	v_pk_mul_f32 v[120:121], v[80:81], v[80:81]
	v_pk_fma_f32 v[104:105], v[124:125], s[22:23], v[100:101] op_sel_hi:[1,0,0]
	v_pk_mul_f32 v[120:121], v[120:121], s[40:41] op_sel_hi:[1,0]
	v_pk_fma_f32 v[104:105], v[124:125], v[104:105], s[26:27] op_sel_hi:[1,1,0]
	v_exp_f32_e32 v120, v120
	v_exp_f32_e32 v121, v121
	v_pk_fma_f32 v[104:105], v[124:125], v[104:105], s[36:37] op_sel_hi:[1,1,0]
	v_pk_fma_f32 v[104:105], v[124:125], v[104:105], s[38:39] op_sel_hi:[1,1,0]
	s_nop 0
	v_pk_mul_f32 v[104:105], v[124:125], v[104:105]
	v_pk_mul_f32 v[124:125], v[82:83], v[82:83]
	v_pk_mul_f32 v[104:105], v[120:121], v[104:105]
	s_nop 0
	v_pk_mul_f32 v[120:121], v[80:81], v[104:105]
	v_max_f32_e32 v126, 0, v80
	v_max_f32_e32 v127, 0, v81
	v_sub_f32_e64 v104, v112, |v106|
	v_sub_f32_e64 v105, v122, |v118|
	v_sub_f32_e64 v106, v113, |v107|
	v_fma_f32 v112, |v82|, s20, 1.0
	v_fma_f32 v113, |v83|, s20, 1.0
	v_sub_f32_e64 v92, v116, |v114|
	v_rcp_f32_e32 v112, v112
	v_rcp_f32_e32 v113, v113
	v_sub_f32_e64 v93, v123, |v119|
	v_cvt_pk_bf16_f32 v108, v104, v106
	v_pk_fma_f32 v[100:101], v[112:113], s[22:23], v[100:101] op_sel_hi:[1,0,0]
	v_sub_f32_e64 v94, v117, |v115|
	v_pk_fma_f32 v[100:101], v[112:113], v[100:101], s[26:27] op_sel_hi:[1,1,0]
	v_sub_f32_e64 v84, v126, |v120|
	v_pk_fma_f32 v[100:101], v[112:113], v[100:101], s[36:37] op_sel_hi:[1,1,0]
	v_sub_f32_e64 v85, v111, |v109|
	v_cvt_pk_bf16_f32 v109, v92, v94
	v_cvt_pk_bf16_f32 v111, v90, v85
	global_store_dwordx4 v[98:99], v[108:111], off
	v_pk_fma_f32 v[100:101], v[112:113], v[100:101], s[38:39] op_sel_hi:[1,1,0]
	s_nop 0
	v_pk_mul_f32 v[108:109], v[124:125], s[40:41] op_sel_hi:[1,0]
	v_pk_mul_f32 v[100:101], v[112:113], v[100:101]
	v_exp_f32_e32 v108, v108
	v_exp_f32_e32 v109, v109
	v_sub_f32_e64 v80, v127, |v121|
	v_cvt_pk_bf16_f32 v110, v84, v80
	v_pk_mul_f32 v[100:101], v[108:109], v[100:101]
	s_nop 0
	v_pk_mul_f32 v[108:109], v[82:83], v[100:101]
	v_max_f32_e32 v100, 0, v82
	v_max_f32_e32 v101, 0, v83
	v_sub_f32_e64 v83, v101, |v109|
	v_cvt_pk_bf16_f32 v109, v103, v87
	v_sub_f32_e64 v82, v100, |v108|
	v_add_co_u32_e32 v98, vcc, 0x820000, v98
	v_cvt_pk_bf16_f32 v108, v105, v93
	s_nop 0
	v_addc_co_u32_e32 v99, vcc, 0, v99, vcc
	v_cvt_pk_bf16_f32 v111, v82, v83
	s_and_b64 vcc, exec, s[6:7]
	global_store_dwordx4 v[98:99], v[108:111], off
	s_cbranch_vccnz .LBB0_185
	v_mov_b32_e32 v107, v105
	v_mov_b32_e32 v81, v85
	v_mov_b32_e32 v95, v93
	v_pk_add_f32 v[98:99], v[84:85], v[80:81]
	v_pk_mul_f32 v[100:101], v[84:85], v[80:81]
	v_mov_b32_e32 v108, v106
	v_pk_add_f32 v[112:113], v[104:105], v[106:107]
	v_pk_mul_f32 v[106:107], v[104:105], v[106:107]
	v_mov_b32_e32 v99, v101
	v_mov_b32_e32 v101, v92
	v_mov_b32_e32 v109, v94
	v_mov_b32_e32 v113, v107
	v_pk_add_f32 v[106:107], v[92:93], v[94:95]
	v_pk_mul_f32 v[94:95], v[92:93], v[94:95]
	v_and_b32_e32 v92, 64, v166
	v_xor_b32_e32 v91, 16, v166
	v_add_u32_e32 v92, 64, v92
	v_mov_b32_e32 v100, v104
	v_pk_mul_f32 v[108:109], v[108:109], v[108:109]
	v_mul_f32_e32 v86, v88, v88
	v_cmp_lt_i32_e32 vcc, v91, v92
	v_pk_fma_f32 v[100:101], v[100:101], v[100:101], v[108:109]
	v_pk_fma_f32 v[108:109], v[88:89], v[88:89], v[86:87] op_sel_hi:[1,1,0]
	v_mul_f32_e32 v86, v82, v82
	v_mov_b32_e32 v107, v95
	v_mul_f32_e32 v95, v103, v103
	v_mul_f32_e32 v115, v87, v87
	v_pk_mul_f32 v[116:117], v[84:85], v[84:85]
	v_pk_mul_f32 v[80:81], v[80:81], v[80:81]
	v_cndmask_b32_e32 v91, v166, v91, vcc
	v_mov_b32_e32 v94, v88
	v_mov_b32_e32 v114, v89
	v_pk_fma_f32 v[110:111], v[82:83], v[82:83], v[86:87] op_sel_hi:[1,1,0]
	v_mov_b32_e32 v102, v105
	v_mov_b32_e32 v86, v93
	v_lshlrev_b32_e32 v93, 2, v91
	v_mov_b32_e32 v91, v116
	v_pk_mov_b32 v[80:81], v[84:85], v[80:81] op_sel:[1,0]
	v_pk_add_f32 v[84:85], v[112:113], v[106:107]
	v_pk_add_f32 v[88:89], v[94:95], v[114:115]
	v_pk_add_f32 v[86:87], v[102:103], v[86:87]
	v_pk_add_f32 v[80:81], v[90:91], v[80:81]
	v_pk_add_f32 v[84:85], v[84:85], v[88:89]
	v_mul_f32_e32 v97, v90, v90
	v_pk_add_f32 v[100:101], v[100:101], v[100:101] op_sel_hi:[0,1]
	v_pk_add_f32 v[80:81], v[84:85], v[80:81]
	v_pk_add_f32 v[84:85], v[86:87], v[86:87] op_sel:[0,1] op_sel_hi:[1,0]
	v_mov_b32_e32 v100, v82
	v_mov_b32_e32 v108, v83
	v_mov_b32_e32 v85, v97
	v_mov_b32_e32 v137, v111
	v_pk_add_f32 v[82:83], v[100:101], v[108:109]
	v_pk_add_f32 v[84:85], v[84:85], v[98:99]
	v_pk_add_f32 v[80:81], v[80:81], v[136:137]
	v_pk_add_f32 v[82:83], v[84:85], v[82:83]
	v_xor_b32_e32 v84, 32, v166
	v_pk_add_f32 v[80:81], v[82:83], v[80:81]
	ds_bpermute_b32 v82, v93, v80
	ds_bpermute_b32 v83, v93, v81
	v_cmp_lt_i32_e32 vcc, v84, v92
	s_waitcnt lgkmcnt(0)
	v_pk_add_f32 v[80:81], v[80:81], v[82:83]
	v_cndmask_b32_e32 v84, v166, v84, vcc
	v_lshlrev_b32_e32 v84, 2, v84
	ds_bpermute_b32 v82, v84, v80
	ds_bpermute_b32 v83, v84, v81
	s_and_saveexec_b64 s[52:53], s[2:3]
	s_cbranch_execz .LBB0_184
	s_lshl_b32 s29, s10, 2
	s_sub_i32 s29, s29, 48
	s_waitcnt lgkmcnt(0)
	v_pk_add_f32 v[80:81], v[80:81], v[82:83]
	v_mov_b32_e32 v82, s29
	v_mov_b32_e32 v83, v136
	v_mad_i64_i32 v[82:83], s[34:35], v96, 48, v[82:83]
	v_or_b32_e32 v82, s61, v82
	v_lshl_add_u64 v[82:83], v[82:83], 3, s[14:15]
	global_store_dwordx2 v[82:83], v[80:81], off

.LBB0_185:
	v_fma_f32 v84, |v76|, s20, 1.0
	v_fma_f32 v85, |v77|, s20, 1.0
	v_pk_mul_f32 v[90:91], v[76:77], v[76:77]
	v_rcp_f32_e32 v86, v84
	v_rcp_f32_e32 v87, v85
	v_mov_b64_e32 v[84:85], s[24:25]
	v_pk_mul_f32 v[90:91], v[90:91], s[40:41] op_sel_hi:[1,0]
	v_pk_fma_f32 v[88:89], v[86:87], s[22:23], v[84:85] op_sel_hi:[1,0,0]
	v_pk_fma_f32 v[88:89], v[86:87], v[88:89], s[26:27] op_sel_hi:[1,1,0]
	v_exp_f32_e32 v90, v90
	v_exp_f32_e32 v91, v91
	v_fma_f32 v92, |v78|, s20, 1.0
	v_fma_f32 v93, |v79|, s20, 1.0
	v_pk_fma_f32 v[88:89], v[86:87], v[88:89], s[36:37] op_sel_hi:[1,1,0]
	v_rcp_f32_e32 v92, v92
	v_rcp_f32_e32 v93, v93
	v_pk_fma_f32 v[88:89], v[86:87], v[88:89], s[38:39] op_sel_hi:[1,1,0]
	v_pk_mul_f32 v[86:87], v[86:87], v[88:89]
	v_pk_mul_f32 v[88:89], v[78:79], v[78:79]
	v_pk_mul_f32 v[86:87], v[90:91], v[86:87]
	v_pk_mul_f32 v[88:89], v[88:89], s[40:41] op_sel_hi:[1,0]
	v_pk_mul_f32 v[90:91], v[76:77], v[86:87]
	v_max_f32_e32 v96, 0, v76
	v_max_f32_e32 v97, 0, v77
	v_pk_fma_f32 v[86:87], v[92:93], s[22:23], v[84:85] op_sel_hi:[1,0,0]
	v_exp_f32_e32 v88, v88
	v_pk_fma_f32 v[86:87], v[92:93], v[86:87], s[26:27] op_sel_hi:[1,1,0]
	v_exp_f32_e32 v89, v89
	v_pk_fma_f32 v[86:87], v[92:93], v[86:87], s[36:37] op_sel_hi:[1,1,0]
	v_pk_fma_f32 v[86:87], v[92:93], v[86:87], s[38:39] op_sel_hi:[1,1,0]
	v_fma_f32 v94, |v74|, s20, 1.0
	v_fma_f32 v95, |v75|, s20, 1.0
	v_pk_mul_f32 v[86:87], v[92:93], v[86:87]
	v_fma_f32 v92, |v72|, s20, 1.0
	v_fma_f32 v93, |v73|, s20, 1.0
	v_pk_mul_f32 v[86:87], v[88:89], v[86:87]
	v_rcp_f32_e32 v92, v92
	v_rcp_f32_e32 v93, v93
	v_pk_mul_f32 v[88:89], v[72:73], v[72:73]
	v_pk_mul_f32 v[98:99], v[78:79], v[86:87]
	v_max_f32_e32 v100, 0, v78
	v_max_f32_e32 v101, 0, v79
	v_pk_fma_f32 v[86:87], v[92:93], s[22:23], v[84:85] op_sel_hi:[1,0,0]
	v_pk_mul_f32 v[88:89], v[88:89], s[40:41] op_sel_hi:[1,0]
	v_pk_fma_f32 v[86:87], v[92:93], v[86:87], s[26:27] op_sel_hi:[1,1,0]
	v_exp_f32_e32 v88, v88
	v_exp_f32_e32 v89, v89
	v_pk_fma_f32 v[86:87], v[92:93], v[86:87], s[36:37] op_sel_hi:[1,1,0]
	v_rcp_f32_e32 v94, v94
	v_pk_fma_f32 v[86:87], v[92:93], v[86:87], s[38:39] op_sel_hi:[1,1,0]
	v_rcp_f32_e32 v95, v95
	v_pk_mul_f32 v[86:87], v[92:93], v[86:87]
	v_pk_mul_f32 v[86:87], v[88:89], v[86:87]
	v_pk_mul_f32 v[92:93], v[74:75], v[74:75]
	v_pk_mul_f32 v[88:89], v[72:73], v[86:87]
	v_max_f32_e32 v86, 0, v72
	v_max_f32_e32 v87, 0, v73
	v_pk_mul_f32 v[102:103], v[68:69], v[68:69]
	v_sub_f32_e64 v73, v87, |v89|
	v_pk_mul_f32 v[102:103], v[102:103], s[40:41] op_sel_hi:[1,0]
	v_sub_f32_e64 v72, v86, |v88|
	v_pk_fma_f32 v[86:87], v[94:95], s[22:23], v[84:85] op_sel_hi:[1,0,0]
	v_pk_mul_f32 v[88:89], v[92:93], s[40:41] op_sel_hi:[1,0]
	v_pk_fma_f32 v[86:87], v[94:95], v[86:87], s[26:27] op_sel_hi:[1,1,0]
	v_exp_f32_e32 v88, v88
	v_exp_f32_e32 v89, v89
	v_pk_fma_f32 v[86:87], v[94:95], v[86:87], s[36:37] op_sel_hi:[1,1,0]
	v_pk_fma_f32 v[86:87], v[94:95], v[86:87], s[38:39] op_sel_hi:[1,1,0]
	v_exp_f32_e32 v102, v102
	v_pk_mul_f32 v[86:87], v[94:95], v[86:87]
	v_exp_f32_e32 v103, v103
	v_pk_mul_f32 v[86:87], v[88:89], v[86:87]
	v_fma_f32 v104, |v70|, s20, 1.0
	v_fma_f32 v105, |v71|, s20, 1.0
	v_pk_mul_f32 v[92:93], v[74:75], v[86:87]
	v_max_f32_e32 v94, 0, v74
	v_max_f32_e32 v95, 0, v75
	v_fma_f32 v86, |v68|, s20, 1.0
	v_fma_f32 v87, |v69|, s20, 1.0
	v_rcp_f32_e32 v104, v104
	v_rcp_f32_e32 v86, v86
	v_rcp_f32_e32 v87, v87
	v_rcp_f32_e32 v105, v105
	v_or_b32_e32 v80, 48, v148
	v_pk_fma_f32 v[88:89], v[86:87], s[22:23], v[84:85] op_sel_hi:[1,0,0]
	v_sub_f32_e64 v74, v94, |v92|
	v_pk_fma_f32 v[88:89], v[86:87], v[88:89], s[26:27] op_sel_hi:[1,1,0]
	v_pk_fma_f32 v[88:89], v[86:87], v[88:89], s[36:37] op_sel_hi:[1,1,0]
	v_ashrrev_i32_e32 v81, 31, v80
	v_pk_fma_f32 v[88:89], v[86:87], v[88:89], s[38:39] op_sel_hi:[1,1,0]
	s_waitcnt lgkmcnt(0)
	v_lshl_add_u64 v[82:83], s[50:51], 0, v[80:81]
	v_pk_mul_f32 v[86:87], v[86:87], v[88:89]
	v_pk_mul_f32 v[88:89], v[70:71], v[70:71]
	v_pk_mul_f32 v[86:87], v[102:103], v[86:87]
	v_pk_mul_f32 v[88:89], v[88:89], s[40:41] op_sel_hi:[1,0]
	v_pk_mul_f32 v[102:103], v[68:69], v[86:87]
	v_max_f32_e32 v106, 0, v68
	v_max_f32_e32 v107, 0, v69
	v_pk_fma_f32 v[86:87], v[104:105], s[22:23], v[84:85] op_sel_hi:[1,0,0]
	v_exp_f32_e32 v88, v88
	v_pk_fma_f32 v[86:87], v[104:105], v[86:87], s[26:27] op_sel_hi:[1,1,0]
	v_exp_f32_e32 v89, v89
	v_pk_fma_f32 v[86:87], v[104:105], v[86:87], s[36:37] op_sel_hi:[1,1,0]
	v_lshlrev_b64 v[82:83], 8, v[82:83]
	v_pk_fma_f32 v[86:87], v[104:105], v[86:87], s[38:39] op_sel_hi:[1,1,0]
	v_lshl_add_u64 v[82:83], v[138:139], 0, v[82:83]
	v_pk_mul_f32 v[86:87], v[104:105], v[86:87]
	v_cvt_pk_bf16_f32 v94, v72, v73
	v_pk_mul_f32 v[86:87], v[88:89], v[86:87]
	s_nop 0
	v_pk_mul_f32 v[88:89], v[70:71], v[86:87]
	v_max_f32_e32 v104, 0, v70
	v_max_f32_e32 v105, 0, v71
	v_fma_f32 v86, |v64|, s20, 1.0
	v_fma_f32 v87, |v65|, s20, 1.0
	s_nop 0
	v_rcp_f32_e32 v108, v86
	v_rcp_f32_e32 v109, v87
	v_sub_f32_e64 v87, v104, |v88|
	v_sub_f32_e64 v71, v105, |v89|
	v_pk_mul_f32 v[104:105], v[64:65], v[64:65]
	v_pk_fma_f32 v[88:89], v[108:109], s[22:23], v[84:85] op_sel_hi:[1,0,0]
	v_pk_mul_f32 v[104:105], v[104:105], s[40:41] op_sel_hi:[1,0]
	v_pk_fma_f32 v[88:89], v[108:109], v[88:89], s[26:27] op_sel_hi:[1,1,0]
	v_exp_f32_e32 v104, v104
	v_exp_f32_e32 v105, v105
	v_pk_fma_f32 v[88:89], v[108:109], v[88:89], s[36:37] op_sel_hi:[1,1,0]
	v_pk_fma_f32 v[88:89], v[108:109], v[88:89], s[38:39] op_sel_hi:[1,1,0]
	s_nop 0
	v_pk_mul_f32 v[88:89], v[108:109], v[88:89]
	v_pk_mul_f32 v[108:109], v[66:67], v[66:67]
	v_pk_mul_f32 v[88:89], v[104:105], v[88:89]
	s_nop 0
	v_pk_mul_f32 v[104:105], v[64:65], v[88:89]
	v_max_f32_e32 v110, 0, v64
	v_max_f32_e32 v111, 0, v65
	v_sub_f32_e64 v88, v96, |v90|
	v_sub_f32_e64 v89, v106, |v102|
	v_sub_f32_e64 v90, v97, |v91|
	v_fma_f32 v96, |v66|, s20, 1.0
	v_fma_f32 v97, |v67|, s20, 1.0
	v_sub_f32_e64 v76, v100, |v98|
	v_rcp_f32_e32 v96, v96
	v_rcp_f32_e32 v97, v97
	v_sub_f32_e64 v77, v107, |v103|
	v_cvt_pk_bf16_f32 v92, v88, v90
	v_pk_fma_f32 v[84:85], v[96:97], s[22:23], v[84:85] op_sel_hi:[1,0,0]
	v_sub_f32_e64 v78, v101, |v99|
	v_pk_fma_f32 v[84:85], v[96:97], v[84:85], s[26:27] op_sel_hi:[1,1,0]
	v_sub_f32_e64 v68, v110, |v104|
	v_pk_fma_f32 v[84:85], v[96:97], v[84:85], s[36:37] op_sel_hi:[1,1,0]
	v_sub_f32_e64 v69, v95, |v93|
	v_cvt_pk_bf16_f32 v93, v76, v78
	v_cvt_pk_bf16_f32 v95, v74, v69
	global_store_dwordx4 v[82:83], v[92:95], off
	v_pk_fma_f32 v[84:85], v[96:97], v[84:85], s[38:39] op_sel_hi:[1,1,0]
	s_nop 0
	v_pk_mul_f32 v[92:93], v[108:109], s[40:41] op_sel_hi:[1,0]
	v_pk_mul_f32 v[84:85], v[96:97], v[84:85]
	v_exp_f32_e32 v92, v92
	v_exp_f32_e32 v93, v93
	v_sub_f32_e64 v64, v111, |v105|
	v_cvt_pk_bf16_f32 v94, v68, v64
	v_pk_mul_f32 v[84:85], v[92:93], v[84:85]
	s_nop 0
	v_pk_mul_f32 v[92:93], v[66:67], v[84:85]
	v_max_f32_e32 v84, 0, v66
	v_max_f32_e32 v85, 0, v67
	v_sub_f32_e64 v67, v85, |v93|
	v_cvt_pk_bf16_f32 v93, v87, v71
	v_sub_f32_e64 v66, v84, |v92|
	v_add_co_u32_e32 v82, vcc, 0x820000, v82
	v_cvt_pk_bf16_f32 v92, v89, v77
	s_nop 0
	v_addc_co_u32_e32 v83, vcc, 0, v83, vcc
	v_cvt_pk_bf16_f32 v95, v66, v67
	s_and_b64 vcc, exec, s[6:7]
	global_store_dwordx4 v[82:83], v[92:95], off
	s_cbranch_vccnz .LBB0_189
	v_mov_b32_e32 v91, v89
	v_mov_b32_e32 v65, v69
	v_mov_b32_e32 v79, v77
	v_pk_add_f32 v[82:83], v[68:69], v[64:65]
	v_pk_mul_f32 v[84:85], v[68:69], v[64:65]
	v_mov_b32_e32 v92, v90
	v_pk_add_f32 v[96:97], v[88:89], v[90:91]
	v_pk_mul_f32 v[90:91], v[88:89], v[90:91]
	v_mov_b32_e32 v83, v85
	v_mov_b32_e32 v85, v76
	v_mov_b32_e32 v93, v78
	v_mov_b32_e32 v97, v91
	v_pk_add_f32 v[90:91], v[76:77], v[78:79]
	v_pk_mul_f32 v[78:79], v[76:77], v[78:79]
	v_and_b32_e32 v76, 64, v166
	v_xor_b32_e32 v75, 16, v166
	v_add_u32_e32 v76, 64, v76
	v_mov_b32_e32 v84, v88
	v_pk_mul_f32 v[92:93], v[92:93], v[92:93]
	v_mul_f32_e32 v70, v72, v72
	v_cmp_lt_i32_e32 vcc, v75, v76
	v_pk_fma_f32 v[84:85], v[84:85], v[84:85], v[92:93]
	v_pk_fma_f32 v[92:93], v[72:73], v[72:73], v[70:71] op_sel_hi:[1,1,0]
	v_mul_f32_e32 v70, v66, v66
	v_mov_b32_e32 v91, v79
	v_mul_f32_e32 v79, v87, v87
	v_mul_f32_e32 v99, v71, v71
	v_pk_mul_f32 v[100:101], v[68:69], v[68:69]
	v_pk_mul_f32 v[64:65], v[64:65], v[64:65]
	v_cndmask_b32_e32 v75, v166, v75, vcc
	v_mov_b32_e32 v78, v72
	v_mov_b32_e32 v98, v73
	v_pk_fma_f32 v[94:95], v[66:67], v[66:67], v[70:71] op_sel_hi:[1,1,0]
	v_mov_b32_e32 v86, v89
	v_mov_b32_e32 v70, v77
	v_lshlrev_b32_e32 v77, 2, v75
	v_mov_b32_e32 v75, v100
	v_pk_mov_b32 v[64:65], v[68:69], v[64:65] op_sel:[1,0]
	v_pk_add_f32 v[68:69], v[96:97], v[90:91]
	v_pk_add_f32 v[72:73], v[78:79], v[98:99]
	v_pk_add_f32 v[70:71], v[86:87], v[70:71]
	v_pk_add_f32 v[64:65], v[74:75], v[64:65]
	v_pk_add_f32 v[68:69], v[68:69], v[72:73]
	v_mul_f32_e32 v81, v74, v74
	v_pk_add_f32 v[84:85], v[84:85], v[84:85] op_sel_hi:[0,1]
	v_pk_add_f32 v[64:65], v[68:69], v[64:65]
	v_pk_add_f32 v[68:69], v[70:71], v[70:71] op_sel:[0,1] op_sel_hi:[1,0]
	v_mov_b32_e32 v84, v66
	v_mov_b32_e32 v92, v67
	v_mov_b32_e32 v69, v81
	v_mov_b32_e32 v137, v95
	v_pk_add_f32 v[66:67], v[84:85], v[92:93]
	v_pk_add_f32 v[68:69], v[68:69], v[82:83]
	v_pk_add_f32 v[64:65], v[64:65], v[136:137]
	v_pk_add_f32 v[66:67], v[68:69], v[66:67]
	v_xor_b32_e32 v68, 32, v166
	v_pk_add_f32 v[64:65], v[66:67], v[64:65]
	ds_bpermute_b32 v66, v77, v64
	ds_bpermute_b32 v67, v77, v65
	v_cmp_lt_i32_e32 vcc, v68, v76
	s_waitcnt lgkmcnt(0)
	v_pk_add_f32 v[64:65], v[64:65], v[66:67]
	v_cndmask_b32_e32 v68, v166, v68, vcc
	v_lshlrev_b32_e32 v68, 2, v68
	ds_bpermute_b32 v66, v68, v64
	ds_bpermute_b32 v67, v68, v65
	s_and_saveexec_b64 s[52:53], s[2:3]
	s_cbranch_execz .LBB0_188
	s_lshl_b32 s29, s10, 2
	s_sub_i32 s29, s29, 48
	s_waitcnt lgkmcnt(0)
	v_pk_add_f32 v[64:65], v[64:65], v[66:67]
	v_mov_b32_e32 v66, s29
	v_mov_b32_e32 v67, v136
	v_mad_i64_i32 v[66:67], s[34:35], v80, 48, v[66:67]
	v_or_b32_e32 v66, s61, v66
	v_lshl_add_u64 v[66:67], v[66:67], 3, s[14:15]
	global_store_dwordx2 v[66:67], v[64:65], off

.LBB0_189:
	v_fma_f32 v68, |v60|, s20, 1.0
	v_fma_f32 v69, |v61|, s20, 1.0
	v_pk_mul_f32 v[74:75], v[60:61], v[60:61]
	v_rcp_f32_e32 v70, v68
	v_rcp_f32_e32 v71, v69
	v_mov_b64_e32 v[68:69], s[24:25]
	v_pk_mul_f32 v[74:75], v[74:75], s[40:41] op_sel_hi:[1,0]
	v_pk_fma_f32 v[72:73], v[70:71], s[22:23], v[68:69] op_sel_hi:[1,0,0]
	v_pk_fma_f32 v[72:73], v[70:71], v[72:73], s[26:27] op_sel_hi:[1,1,0]
	v_exp_f32_e32 v74, v74
	v_exp_f32_e32 v75, v75
	v_fma_f32 v76, |v62|, s20, 1.0
	v_fma_f32 v77, |v63|, s20, 1.0
	v_pk_fma_f32 v[72:73], v[70:71], v[72:73], s[36:37] op_sel_hi:[1,1,0]
	v_rcp_f32_e32 v76, v76
	v_rcp_f32_e32 v77, v77
	v_pk_fma_f32 v[72:73], v[70:71], v[72:73], s[38:39] op_sel_hi:[1,1,0]
	v_pk_mul_f32 v[70:71], v[70:71], v[72:73]
	v_pk_mul_f32 v[72:73], v[62:63], v[62:63]
	v_pk_mul_f32 v[70:71], v[74:75], v[70:71]
	v_pk_mul_f32 v[72:73], v[72:73], s[40:41] op_sel_hi:[1,0]
	v_pk_mul_f32 v[74:75], v[60:61], v[70:71]
	v_max_f32_e32 v80, 0, v60
	v_max_f32_e32 v81, 0, v61
	v_pk_fma_f32 v[70:71], v[76:77], s[22:23], v[68:69] op_sel_hi:[1,0,0]
	v_exp_f32_e32 v72, v72
	v_pk_fma_f32 v[70:71], v[76:77], v[70:71], s[26:27] op_sel_hi:[1,1,0]
	v_exp_f32_e32 v73, v73
	v_pk_fma_f32 v[70:71], v[76:77], v[70:71], s[36:37] op_sel_hi:[1,1,0]
	v_pk_fma_f32 v[70:71], v[76:77], v[70:71], s[38:39] op_sel_hi:[1,1,0]
	v_fma_f32 v78, |v58|, s20, 1.0
	v_fma_f32 v79, |v59|, s20, 1.0
	v_pk_mul_f32 v[70:71], v[76:77], v[70:71]
	v_fma_f32 v76, |v56|, s20, 1.0
	v_fma_f32 v77, |v57|, s20, 1.0
	v_pk_mul_f32 v[70:71], v[72:73], v[70:71]
	v_rcp_f32_e32 v76, v76
	v_rcp_f32_e32 v77, v77
	v_pk_mul_f32 v[72:73], v[56:57], v[56:57]
	v_pk_mul_f32 v[82:83], v[62:63], v[70:71]
	v_max_f32_e32 v84, 0, v62
	v_max_f32_e32 v85, 0, v63
	v_pk_fma_f32 v[70:71], v[76:77], s[22:23], v[68:69] op_sel_hi:[1,0,0]
	v_pk_mul_f32 v[72:73], v[72:73], s[40:41] op_sel_hi:[1,0]
	v_pk_fma_f32 v[70:71], v[76:77], v[70:71], s[26:27] op_sel_hi:[1,1,0]
	v_exp_f32_e32 v72, v72
	v_exp_f32_e32 v73, v73
	v_pk_fma_f32 v[70:71], v[76:77], v[70:71], s[36:37] op_sel_hi:[1,1,0]
	v_rcp_f32_e32 v78, v78
	v_pk_fma_f32 v[70:71], v[76:77], v[70:71], s[38:39] op_sel_hi:[1,1,0]
	v_rcp_f32_e32 v79, v79
	v_pk_mul_f32 v[70:71], v[76:77], v[70:71]
	v_pk_mul_f32 v[70:71], v[72:73], v[70:71]
	v_pk_mul_f32 v[76:77], v[58:59], v[58:59]
	v_pk_mul_f32 v[72:73], v[56:57], v[70:71]
	v_max_f32_e32 v70, 0, v56
	v_max_f32_e32 v71, 0, v57
	v_pk_mul_f32 v[86:87], v[52:53], v[52:53]
	v_sub_f32_e64 v57, v71, |v73|
	v_pk_mul_f32 v[86:87], v[86:87], s[40:41] op_sel_hi:[1,0]
	v_sub_f32_e64 v56, v70, |v72|
	v_pk_fma_f32 v[70:71], v[78:79], s[22:23], v[68:69] op_sel_hi:[1,0,0]
	v_pk_mul_f32 v[72:73], v[76:77], s[40:41] op_sel_hi:[1,0]
	v_pk_fma_f32 v[70:71], v[78:79], v[70:71], s[26:27] op_sel_hi:[1,1,0]
	v_exp_f32_e32 v72, v72
	v_exp_f32_e32 v73, v73
	v_pk_fma_f32 v[70:71], v[78:79], v[70:71], s[36:37] op_sel_hi:[1,1,0]
	v_pk_fma_f32 v[70:71], v[78:79], v[70:71], s[38:39] op_sel_hi:[1,1,0]
	v_exp_f32_e32 v86, v86
	v_pk_mul_f32 v[70:71], v[78:79], v[70:71]
	v_exp_f32_e32 v87, v87
	v_pk_mul_f32 v[70:71], v[72:73], v[70:71]
	v_fma_f32 v88, |v54|, s20, 1.0
	v_fma_f32 v89, |v55|, s20, 1.0
	v_pk_mul_f32 v[76:77], v[58:59], v[70:71]
	v_max_f32_e32 v78, 0, v58
	v_max_f32_e32 v79, 0, v59
	v_fma_f32 v70, |v52|, s20, 1.0
	v_fma_f32 v71, |v53|, s20, 1.0
	v_rcp_f32_e32 v88, v88
	v_rcp_f32_e32 v70, v70
	v_rcp_f32_e32 v71, v71
	v_rcp_f32_e32 v89, v89
	v_add_u32_e32 v64, 0x80, v148
	v_pk_fma_f32 v[72:73], v[70:71], s[22:23], v[68:69] op_sel_hi:[1,0,0]
	v_sub_f32_e64 v58, v78, |v76|
	v_pk_fma_f32 v[72:73], v[70:71], v[72:73], s[26:27] op_sel_hi:[1,1,0]
	v_pk_fma_f32 v[72:73], v[70:71], v[72:73], s[36:37] op_sel_hi:[1,1,0]
	v_ashrrev_i32_e32 v65, 31, v64
	v_pk_fma_f32 v[72:73], v[70:71], v[72:73], s[38:39] op_sel_hi:[1,1,0]
	s_waitcnt lgkmcnt(0)
	v_lshl_add_u64 v[66:67], s[50:51], 0, v[64:65]
	v_pk_mul_f32 v[70:71], v[70:71], v[72:73]
	v_pk_mul_f32 v[72:73], v[54:55], v[54:55]
	v_pk_mul_f32 v[70:71], v[86:87], v[70:71]
	v_pk_mul_f32 v[72:73], v[72:73], s[40:41] op_sel_hi:[1,0]
	v_pk_mul_f32 v[86:87], v[52:53], v[70:71]
	v_max_f32_e32 v90, 0, v52
	v_max_f32_e32 v91, 0, v53
	v_pk_fma_f32 v[70:71], v[88:89], s[22:23], v[68:69] op_sel_hi:[1,0,0]
	v_exp_f32_e32 v72, v72
	v_pk_fma_f32 v[70:71], v[88:89], v[70:71], s[26:27] op_sel_hi:[1,1,0]
	v_exp_f32_e32 v73, v73
	v_pk_fma_f32 v[70:71], v[88:89], v[70:71], s[36:37] op_sel_hi:[1,1,0]
	v_lshlrev_b64 v[66:67], 8, v[66:67]
	v_pk_fma_f32 v[70:71], v[88:89], v[70:71], s[38:39] op_sel_hi:[1,1,0]
	v_lshl_add_u64 v[66:67], v[138:139], 0, v[66:67]
	v_pk_mul_f32 v[70:71], v[88:89], v[70:71]
	v_cvt_pk_bf16_f32 v78, v56, v57
	v_pk_mul_f32 v[70:71], v[72:73], v[70:71]
	s_nop 0
	v_pk_mul_f32 v[72:73], v[54:55], v[70:71]
	v_max_f32_e32 v88, 0, v54
	v_max_f32_e32 v89, 0, v55
	v_fma_f32 v70, |v48|, s20, 1.0
	v_fma_f32 v71, |v49|, s20, 1.0
	s_nop 0
	v_rcp_f32_e32 v92, v70
	v_rcp_f32_e32 v93, v71
	v_sub_f32_e64 v71, v88, |v72|
	v_sub_f32_e64 v55, v89, |v73|
	v_pk_mul_f32 v[88:89], v[48:49], v[48:49]
	v_pk_fma_f32 v[72:73], v[92:93], s[22:23], v[68:69] op_sel_hi:[1,0,0]
	v_pk_mul_f32 v[88:89], v[88:89], s[40:41] op_sel_hi:[1,0]
	v_pk_fma_f32 v[72:73], v[92:93], v[72:73], s[26:27] op_sel_hi:[1,1,0]
	v_exp_f32_e32 v88, v88
	v_exp_f32_e32 v89, v89
	v_pk_fma_f32 v[72:73], v[92:93], v[72:73], s[36:37] op_sel_hi:[1,1,0]
	v_pk_fma_f32 v[72:73], v[92:93], v[72:73], s[38:39] op_sel_hi:[1,1,0]
	s_nop 0
	v_pk_mul_f32 v[72:73], v[92:93], v[72:73]
	v_pk_mul_f32 v[92:93], v[50:51], v[50:51]
	v_pk_mul_f32 v[72:73], v[88:89], v[72:73]
	s_nop 0
	v_pk_mul_f32 v[88:89], v[48:49], v[72:73]
	v_max_f32_e32 v94, 0, v48
	v_max_f32_e32 v95, 0, v49
	v_sub_f32_e64 v72, v80, |v74|
	v_sub_f32_e64 v73, v90, |v86|
	v_sub_f32_e64 v74, v81, |v75|
	v_fma_f32 v80, |v50|, s20, 1.0
	v_fma_f32 v81, |v51|, s20, 1.0
	v_sub_f32_e64 v60, v84, |v82|
	v_rcp_f32_e32 v80, v80
	v_rcp_f32_e32 v81, v81
	v_sub_f32_e64 v61, v91, |v87|
	v_cvt_pk_bf16_f32 v76, v72, v74
	v_pk_fma_f32 v[68:69], v[80:81], s[22:23], v[68:69] op_sel_hi:[1,0,0]
	v_sub_f32_e64 v62, v85, |v83|
	v_pk_fma_f32 v[68:69], v[80:81], v[68:69], s[26:27] op_sel_hi:[1,1,0]
	v_sub_f32_e64 v52, v94, |v88|
	v_pk_fma_f32 v[68:69], v[80:81], v[68:69], s[36:37] op_sel_hi:[1,1,0]
	v_sub_f32_e64 v53, v79, |v77|
	v_cvt_pk_bf16_f32 v77, v60, v62
	v_cvt_pk_bf16_f32 v79, v58, v53
	global_store_dwordx4 v[66:67], v[76:79], off
	v_pk_fma_f32 v[68:69], v[80:81], v[68:69], s[38:39] op_sel_hi:[1,1,0]
	s_nop 0
	v_pk_mul_f32 v[76:77], v[92:93], s[40:41] op_sel_hi:[1,0]
	v_pk_mul_f32 v[68:69], v[80:81], v[68:69]
	v_exp_f32_e32 v76, v76
	v_exp_f32_e32 v77, v77
	v_sub_f32_e64 v48, v95, |v89|
	v_cvt_pk_bf16_f32 v78, v52, v48
	v_pk_mul_f32 v[68:69], v[76:77], v[68:69]
	s_nop 0
	v_pk_mul_f32 v[76:77], v[50:51], v[68:69]
	v_max_f32_e32 v68, 0, v50
	v_max_f32_e32 v69, 0, v51
	v_sub_f32_e64 v51, v69, |v77|
	v_cvt_pk_bf16_f32 v77, v71, v55
	v_sub_f32_e64 v50, v68, |v76|
	v_add_co_u32_e32 v66, vcc, 0x820000, v66
	v_cvt_pk_bf16_f32 v76, v73, v61
	s_nop 0
	v_addc_co_u32_e32 v67, vcc, 0, v67, vcc
	v_cvt_pk_bf16_f32 v79, v50, v51
	s_and_b64 vcc, exec, s[6:7]
	global_store_dwordx4 v[66:67], v[76:79], off
	s_cbranch_vccnz .LBB0_193
	v_mov_b32_e32 v75, v73
	v_mov_b32_e32 v49, v53
	v_mov_b32_e32 v63, v61
	v_pk_add_f32 v[66:67], v[52:53], v[48:49]
	v_pk_mul_f32 v[68:69], v[52:53], v[48:49]
	v_mov_b32_e32 v76, v74
	v_pk_add_f32 v[80:81], v[72:73], v[74:75]
	v_pk_mul_f32 v[74:75], v[72:73], v[74:75]
	v_mov_b32_e32 v67, v69
	v_mov_b32_e32 v69, v60
	v_mov_b32_e32 v77, v62
	v_mov_b32_e32 v81, v75
	v_pk_add_f32 v[74:75], v[60:61], v[62:63]
	v_pk_mul_f32 v[62:63], v[60:61], v[62:63]
	v_and_b32_e32 v60, 64, v166
	v_xor_b32_e32 v59, 16, v166
	v_add_u32_e32 v60, 64, v60
	v_mov_b32_e32 v68, v72
	v_pk_mul_f32 v[76:77], v[76:77], v[76:77]
	v_mul_f32_e32 v54, v56, v56
	v_cmp_lt_i32_e32 vcc, v59, v60
	v_pk_fma_f32 v[68:69], v[68:69], v[68:69], v[76:77]
	v_pk_fma_f32 v[76:77], v[56:57], v[56:57], v[54:55] op_sel_hi:[1,1,0]
	v_mul_f32_e32 v54, v50, v50
	v_mov_b32_e32 v75, v63
	v_mul_f32_e32 v63, v71, v71
	v_mul_f32_e32 v83, v55, v55
	v_pk_mul_f32 v[84:85], v[52:53], v[52:53]
	v_pk_mul_f32 v[48:49], v[48:49], v[48:49]
	v_cndmask_b32_e32 v59, v166, v59, vcc
	v_mov_b32_e32 v62, v56
	v_mov_b32_e32 v82, v57
	v_pk_fma_f32 v[78:79], v[50:51], v[50:51], v[54:55] op_sel_hi:[1,1,0]
	v_mov_b32_e32 v70, v73
	v_mov_b32_e32 v54, v61
	v_lshlrev_b32_e32 v61, 2, v59
	v_mov_b32_e32 v59, v84
	v_pk_mov_b32 v[48:49], v[52:53], v[48:49] op_sel:[1,0]
	v_pk_add_f32 v[52:53], v[80:81], v[74:75]
	v_pk_add_f32 v[56:57], v[62:63], v[82:83]
	v_pk_add_f32 v[54:55], v[70:71], v[54:55]
	v_pk_add_f32 v[48:49], v[58:59], v[48:49]
	v_pk_add_f32 v[52:53], v[52:53], v[56:57]
	v_mul_f32_e32 v65, v58, v58
	v_pk_add_f32 v[68:69], v[68:69], v[68:69] op_sel_hi:[0,1]
	v_pk_add_f32 v[48:49], v[52:53], v[48:49]
	v_pk_add_f32 v[52:53], v[54:55], v[54:55] op_sel:[0,1] op_sel_hi:[1,0]
	v_mov_b32_e32 v68, v50
	v_mov_b32_e32 v76, v51
	v_mov_b32_e32 v53, v65
	v_mov_b32_e32 v137, v79
	v_pk_add_f32 v[50:51], v[68:69], v[76:77]
	v_pk_add_f32 v[52:53], v[52:53], v[66:67]
	v_pk_add_f32 v[48:49], v[48:49], v[136:137]
	v_pk_add_f32 v[50:51], v[52:53], v[50:51]
	v_xor_b32_e32 v52, 32, v166
	v_pk_add_f32 v[48:49], v[50:51], v[48:49]
	ds_bpermute_b32 v50, v61, v48
	ds_bpermute_b32 v51, v61, v49
	v_cmp_lt_i32_e32 vcc, v52, v60
	s_waitcnt lgkmcnt(0)
	v_pk_add_f32 v[48:49], v[48:49], v[50:51]
	v_cndmask_b32_e32 v52, v166, v52, vcc
	v_lshlrev_b32_e32 v52, 2, v52
	ds_bpermute_b32 v50, v52, v48
	ds_bpermute_b32 v51, v52, v49
	s_and_saveexec_b64 s[52:53], s[2:3]
	s_cbranch_execz .LBB0_192
	s_lshl_b32 s29, s10, 2
	s_sub_i32 s29, s29, 48
	s_waitcnt lgkmcnt(0)
	v_pk_add_f32 v[48:49], v[48:49], v[50:51]
	v_mov_b32_e32 v50, s29
	v_mov_b32_e32 v51, v136
	v_mad_i64_i32 v[50:51], s[34:35], v64, 48, v[50:51]
	v_or_b32_e32 v50, s61, v50
	v_lshl_add_u64 v[50:51], v[50:51], 3, s[14:15]
	global_store_dwordx2 v[50:51], v[48:49], off

.LBB0_193:
	v_fma_f32 v52, |v44|, s20, 1.0
	v_fma_f32 v53, |v45|, s20, 1.0
	v_pk_mul_f32 v[58:59], v[44:45], v[44:45]
	v_rcp_f32_e32 v54, v52
	v_rcp_f32_e32 v55, v53
	v_mov_b64_e32 v[52:53], s[24:25]
	v_pk_mul_f32 v[58:59], v[58:59], s[40:41] op_sel_hi:[1,0]
	v_pk_fma_f32 v[56:57], v[54:55], s[22:23], v[52:53] op_sel_hi:[1,0,0]
	v_pk_fma_f32 v[56:57], v[54:55], v[56:57], s[26:27] op_sel_hi:[1,1,0]
	v_exp_f32_e32 v58, v58
	v_exp_f32_e32 v59, v59
	v_fma_f32 v60, |v46|, s20, 1.0
	v_fma_f32 v61, |v47|, s20, 1.0
	v_pk_fma_f32 v[56:57], v[54:55], v[56:57], s[36:37] op_sel_hi:[1,1,0]
	v_rcp_f32_e32 v60, v60
	v_rcp_f32_e32 v61, v61
	v_pk_fma_f32 v[56:57], v[54:55], v[56:57], s[38:39] op_sel_hi:[1,1,0]
	v_pk_mul_f32 v[54:55], v[54:55], v[56:57]
	v_pk_mul_f32 v[56:57], v[46:47], v[46:47]
	v_pk_mul_f32 v[54:55], v[58:59], v[54:55]
	v_pk_mul_f32 v[56:57], v[56:57], s[40:41] op_sel_hi:[1,0]
	v_pk_mul_f32 v[58:59], v[44:45], v[54:55]
	v_max_f32_e32 v64, 0, v44
	v_max_f32_e32 v65, 0, v45
	v_pk_fma_f32 v[54:55], v[60:61], s[22:23], v[52:53] op_sel_hi:[1,0,0]
	v_exp_f32_e32 v56, v56
	v_pk_fma_f32 v[54:55], v[60:61], v[54:55], s[26:27] op_sel_hi:[1,1,0]
	v_exp_f32_e32 v57, v57
	v_pk_fma_f32 v[54:55], v[60:61], v[54:55], s[36:37] op_sel_hi:[1,1,0]
	v_pk_fma_f32 v[54:55], v[60:61], v[54:55], s[38:39] op_sel_hi:[1,1,0]
	v_fma_f32 v62, |v42|, s20, 1.0
	v_fma_f32 v63, |v43|, s20, 1.0
	v_pk_mul_f32 v[54:55], v[60:61], v[54:55]
	v_fma_f32 v60, |v40|, s20, 1.0
	v_fma_f32 v61, |v41|, s20, 1.0
	v_pk_mul_f32 v[54:55], v[56:57], v[54:55]
	v_rcp_f32_e32 v60, v60
	v_rcp_f32_e32 v61, v61
	v_pk_mul_f32 v[56:57], v[40:41], v[40:41]
	v_pk_mul_f32 v[66:67], v[46:47], v[54:55]
	v_max_f32_e32 v68, 0, v46
	v_max_f32_e32 v69, 0, v47
	v_pk_fma_f32 v[54:55], v[60:61], s[22:23], v[52:53] op_sel_hi:[1,0,0]
	v_pk_mul_f32 v[56:57], v[56:57], s[40:41] op_sel_hi:[1,0]
	v_pk_fma_f32 v[54:55], v[60:61], v[54:55], s[26:27] op_sel_hi:[1,1,0]
	v_exp_f32_e32 v56, v56
	v_exp_f32_e32 v57, v57
	v_pk_fma_f32 v[54:55], v[60:61], v[54:55], s[36:37] op_sel_hi:[1,1,0]
	v_rcp_f32_e32 v62, v62
	v_pk_fma_f32 v[54:55], v[60:61], v[54:55], s[38:39] op_sel_hi:[1,1,0]
	v_rcp_f32_e32 v63, v63
	v_pk_mul_f32 v[54:55], v[60:61], v[54:55]
	v_pk_mul_f32 v[54:55], v[56:57], v[54:55]
	v_pk_mul_f32 v[60:61], v[42:43], v[42:43]
	v_pk_mul_f32 v[56:57], v[40:41], v[54:55]
	v_max_f32_e32 v54, 0, v40
	v_max_f32_e32 v55, 0, v41
	v_pk_mul_f32 v[70:71], v[36:37], v[36:37]
	v_sub_f32_e64 v41, v55, |v57|
	v_pk_mul_f32 v[70:71], v[70:71], s[40:41] op_sel_hi:[1,0]
	v_sub_f32_e64 v40, v54, |v56|
	v_pk_fma_f32 v[54:55], v[62:63], s[22:23], v[52:53] op_sel_hi:[1,0,0]
	v_pk_mul_f32 v[56:57], v[60:61], s[40:41] op_sel_hi:[1,0]
	v_pk_fma_f32 v[54:55], v[62:63], v[54:55], s[26:27] op_sel_hi:[1,1,0]
	v_exp_f32_e32 v56, v56
	v_exp_f32_e32 v57, v57
	v_pk_fma_f32 v[54:55], v[62:63], v[54:55], s[36:37] op_sel_hi:[1,1,0]
	v_pk_fma_f32 v[54:55], v[62:63], v[54:55], s[38:39] op_sel_hi:[1,1,0]
	v_exp_f32_e32 v70, v70
	v_pk_mul_f32 v[54:55], v[62:63], v[54:55]
	v_exp_f32_e32 v71, v71
	v_pk_mul_f32 v[54:55], v[56:57], v[54:55]
	v_fma_f32 v72, |v38|, s20, 1.0
	v_fma_f32 v73, |v39|, s20, 1.0
	v_pk_mul_f32 v[60:61], v[42:43], v[54:55]
	v_max_f32_e32 v62, 0, v42
	v_max_f32_e32 v63, 0, v43
	v_fma_f32 v54, |v36|, s20, 1.0
	v_fma_f32 v55, |v37|, s20, 1.0
	v_rcp_f32_e32 v72, v72
	v_rcp_f32_e32 v54, v54
	v_rcp_f32_e32 v55, v55
	v_rcp_f32_e32 v73, v73
	v_add_u32_e32 v48, 0x90, v148
	v_pk_fma_f32 v[56:57], v[54:55], s[22:23], v[52:53] op_sel_hi:[1,0,0]
	v_sub_f32_e64 v42, v62, |v60|
	v_pk_fma_f32 v[56:57], v[54:55], v[56:57], s[26:27] op_sel_hi:[1,1,0]
	v_pk_fma_f32 v[56:57], v[54:55], v[56:57], s[36:37] op_sel_hi:[1,1,0]
	v_ashrrev_i32_e32 v49, 31, v48
	v_pk_fma_f32 v[56:57], v[54:55], v[56:57], s[38:39] op_sel_hi:[1,1,0]
	s_waitcnt lgkmcnt(0)
	v_lshl_add_u64 v[50:51], s[50:51], 0, v[48:49]
	v_pk_mul_f32 v[54:55], v[54:55], v[56:57]
	v_pk_mul_f32 v[56:57], v[38:39], v[38:39]
	v_pk_mul_f32 v[54:55], v[70:71], v[54:55]
	v_pk_mul_f32 v[56:57], v[56:57], s[40:41] op_sel_hi:[1,0]
	v_pk_mul_f32 v[70:71], v[36:37], v[54:55]
	v_max_f32_e32 v74, 0, v36
	v_max_f32_e32 v75, 0, v37
	v_pk_fma_f32 v[54:55], v[72:73], s[22:23], v[52:53] op_sel_hi:[1,0,0]
	v_exp_f32_e32 v56, v56
	v_pk_fma_f32 v[54:55], v[72:73], v[54:55], s[26:27] op_sel_hi:[1,1,0]
	v_exp_f32_e32 v57, v57
	v_pk_fma_f32 v[54:55], v[72:73], v[54:55], s[36:37] op_sel_hi:[1,1,0]
	v_lshlrev_b64 v[50:51], 8, v[50:51]
	v_pk_fma_f32 v[54:55], v[72:73], v[54:55], s[38:39] op_sel_hi:[1,1,0]
	v_lshl_add_u64 v[50:51], v[138:139], 0, v[50:51]
	v_pk_mul_f32 v[54:55], v[72:73], v[54:55]
	v_cvt_pk_bf16_f32 v62, v40, v41
	v_pk_mul_f32 v[54:55], v[56:57], v[54:55]
	s_nop 0
	v_pk_mul_f32 v[56:57], v[38:39], v[54:55]
	v_max_f32_e32 v72, 0, v38
	v_max_f32_e32 v73, 0, v39
	v_fma_f32 v54, |v32|, s20, 1.0
	v_fma_f32 v55, |v33|, s20, 1.0
	s_nop 0
	v_rcp_f32_e32 v76, v54
	v_rcp_f32_e32 v77, v55
	v_sub_f32_e64 v55, v72, |v56|
	v_sub_f32_e64 v39, v73, |v57|
	v_pk_mul_f32 v[72:73], v[32:33], v[32:33]
	v_pk_fma_f32 v[56:57], v[76:77], s[22:23], v[52:53] op_sel_hi:[1,0,0]
	v_pk_mul_f32 v[72:73], v[72:73], s[40:41] op_sel_hi:[1,0]
	v_pk_fma_f32 v[56:57], v[76:77], v[56:57], s[26:27] op_sel_hi:[1,1,0]
	v_exp_f32_e32 v72, v72
	v_exp_f32_e32 v73, v73
	v_pk_fma_f32 v[56:57], v[76:77], v[56:57], s[36:37] op_sel_hi:[1,1,0]
	v_pk_fma_f32 v[56:57], v[76:77], v[56:57], s[38:39] op_sel_hi:[1,1,0]
	s_nop 0
	v_pk_mul_f32 v[56:57], v[76:77], v[56:57]
	v_pk_mul_f32 v[76:77], v[34:35], v[34:35]
	v_pk_mul_f32 v[56:57], v[72:73], v[56:57]
	s_nop 0
	v_pk_mul_f32 v[72:73], v[32:33], v[56:57]
	v_max_f32_e32 v78, 0, v32
	v_max_f32_e32 v79, 0, v33
	v_sub_f32_e64 v56, v64, |v58|
	v_sub_f32_e64 v57, v74, |v70|
	v_sub_f32_e64 v58, v65, |v59|
	v_fma_f32 v64, |v34|, s20, 1.0
	v_fma_f32 v65, |v35|, s20, 1.0
	v_sub_f32_e64 v44, v68, |v66|
	v_rcp_f32_e32 v64, v64
	v_rcp_f32_e32 v65, v65
	v_sub_f32_e64 v45, v75, |v71|
	v_cvt_pk_bf16_f32 v60, v56, v58
	v_pk_fma_f32 v[52:53], v[64:65], s[22:23], v[52:53] op_sel_hi:[1,0,0]
	v_sub_f32_e64 v46, v69, |v67|
	v_pk_fma_f32 v[52:53], v[64:65], v[52:53], s[26:27] op_sel_hi:[1,1,0]
	v_sub_f32_e64 v36, v78, |v72|
	v_pk_fma_f32 v[52:53], v[64:65], v[52:53], s[36:37] op_sel_hi:[1,1,0]
	v_sub_f32_e64 v37, v63, |v61|
	v_cvt_pk_bf16_f32 v61, v44, v46
	v_cvt_pk_bf16_f32 v63, v42, v37
	global_store_dwordx4 v[50:51], v[60:63], off
	v_pk_fma_f32 v[52:53], v[64:65], v[52:53], s[38:39] op_sel_hi:[1,1,0]
	s_nop 0
	v_pk_mul_f32 v[60:61], v[76:77], s[40:41] op_sel_hi:[1,0]
	v_pk_mul_f32 v[52:53], v[64:65], v[52:53]
	v_exp_f32_e32 v60, v60
	v_exp_f32_e32 v61, v61
	v_sub_f32_e64 v32, v79, |v73|
	v_cvt_pk_bf16_f32 v62, v36, v32
	v_pk_mul_f32 v[52:53], v[60:61], v[52:53]
	s_nop 0
	v_pk_mul_f32 v[60:61], v[34:35], v[52:53]
	v_max_f32_e32 v52, 0, v34
	v_max_f32_e32 v53, 0, v35
	v_sub_f32_e64 v35, v53, |v61|
	v_cvt_pk_bf16_f32 v61, v55, v39
	v_sub_f32_e64 v34, v52, |v60|
	v_add_co_u32_e32 v50, vcc, 0x820000, v50
	v_cvt_pk_bf16_f32 v60, v57, v45
	s_nop 0
	v_addc_co_u32_e32 v51, vcc, 0, v51, vcc
	v_cvt_pk_bf16_f32 v63, v34, v35
	s_and_b64 vcc, exec, s[6:7]
	global_store_dwordx4 v[50:51], v[60:63], off
	s_cbranch_vccnz .LBB0_197
	v_mov_b32_e32 v59, v57
	v_mov_b32_e32 v33, v37
	v_mov_b32_e32 v47, v45
	v_pk_add_f32 v[50:51], v[36:37], v[32:33]
	v_pk_mul_f32 v[52:53], v[36:37], v[32:33]
	v_mov_b32_e32 v60, v58
	v_pk_add_f32 v[64:65], v[56:57], v[58:59]
	v_pk_mul_f32 v[58:59], v[56:57], v[58:59]
	v_mov_b32_e32 v51, v53
	v_mov_b32_e32 v53, v44
	v_mov_b32_e32 v61, v46
	v_mov_b32_e32 v65, v59
	v_pk_add_f32 v[58:59], v[44:45], v[46:47]
	v_pk_mul_f32 v[46:47], v[44:45], v[46:47]
	v_and_b32_e32 v44, 64, v166
	v_xor_b32_e32 v43, 16, v166
	v_add_u32_e32 v44, 64, v44
	v_mov_b32_e32 v52, v56
	v_pk_mul_f32 v[60:61], v[60:61], v[60:61]
	v_mul_f32_e32 v38, v40, v40
	v_cmp_lt_i32_e32 vcc, v43, v44
	v_pk_fma_f32 v[52:53], v[52:53], v[52:53], v[60:61]
	v_pk_fma_f32 v[60:61], v[40:41], v[40:41], v[38:39] op_sel_hi:[1,1,0]
	v_mul_f32_e32 v38, v34, v34
	v_mov_b32_e32 v59, v47
	v_mul_f32_e32 v47, v55, v55
	v_mul_f32_e32 v67, v39, v39
	v_pk_mul_f32 v[68:69], v[36:37], v[36:37]
	v_pk_mul_f32 v[32:33], v[32:33], v[32:33]
	v_cndmask_b32_e32 v43, v166, v43, vcc
	v_mov_b32_e32 v46, v40
	v_mov_b32_e32 v66, v41
	v_pk_fma_f32 v[62:63], v[34:35], v[34:35], v[38:39] op_sel_hi:[1,1,0]
	v_mov_b32_e32 v54, v57
	v_mov_b32_e32 v38, v45
	v_lshlrev_b32_e32 v45, 2, v43
	v_mov_b32_e32 v43, v68
	v_pk_mov_b32 v[32:33], v[36:37], v[32:33] op_sel:[1,0]
	v_pk_add_f32 v[36:37], v[64:65], v[58:59]
	v_pk_add_f32 v[40:41], v[46:47], v[66:67]
	v_pk_add_f32 v[38:39], v[54:55], v[38:39]
	v_pk_add_f32 v[32:33], v[42:43], v[32:33]
	v_pk_add_f32 v[36:37], v[36:37], v[40:41]
	v_mul_f32_e32 v49, v42, v42
	v_pk_add_f32 v[52:53], v[52:53], v[52:53] op_sel_hi:[0,1]
	v_pk_add_f32 v[32:33], v[36:37], v[32:33]
	v_pk_add_f32 v[36:37], v[38:39], v[38:39] op_sel:[0,1] op_sel_hi:[1,0]
	v_mov_b32_e32 v52, v34
	v_mov_b32_e32 v60, v35
	v_mov_b32_e32 v37, v49
	v_mov_b32_e32 v137, v63
	v_pk_add_f32 v[34:35], v[52:53], v[60:61]
	v_pk_add_f32 v[36:37], v[36:37], v[50:51]
	v_pk_add_f32 v[32:33], v[32:33], v[136:137]
	v_pk_add_f32 v[34:35], v[36:37], v[34:35]
	v_xor_b32_e32 v36, 32, v166
	v_pk_add_f32 v[32:33], v[34:35], v[32:33]
	ds_bpermute_b32 v34, v45, v32
	ds_bpermute_b32 v35, v45, v33
	v_cmp_lt_i32_e32 vcc, v36, v44
	s_waitcnt lgkmcnt(0)
	v_pk_add_f32 v[32:33], v[32:33], v[34:35]
	v_cndmask_b32_e32 v36, v166, v36, vcc
	v_lshlrev_b32_e32 v36, 2, v36
	ds_bpermute_b32 v34, v36, v32
	ds_bpermute_b32 v35, v36, v33
	s_and_saveexec_b64 s[52:53], s[2:3]
	s_cbranch_execz .LBB0_196
	s_lshl_b32 s29, s10, 2
	s_sub_i32 s29, s29, 48
	s_waitcnt lgkmcnt(0)
	v_pk_add_f32 v[32:33], v[32:33], v[34:35]
	v_mov_b32_e32 v34, s29
	v_mov_b32_e32 v35, v136
	v_mad_i64_i32 v[34:35], s[34:35], v48, 48, v[34:35]
	v_or_b32_e32 v34, s61, v34
	v_lshl_add_u64 v[34:35], v[34:35], 3, s[14:15]
	global_store_dwordx2 v[34:35], v[32:33], off

.LBB0_197:
	v_fma_f32 v36, |v28|, s20, 1.0
	v_fma_f32 v37, |v29|, s20, 1.0
	v_pk_mul_f32 v[42:43], v[28:29], v[28:29]
	v_rcp_f32_e32 v38, v36
	v_rcp_f32_e32 v39, v37
	v_mov_b64_e32 v[36:37], s[24:25]
	v_pk_mul_f32 v[42:43], v[42:43], s[40:41] op_sel_hi:[1,0]
	v_pk_fma_f32 v[40:41], v[38:39], s[22:23], v[36:37] op_sel_hi:[1,0,0]
	v_pk_fma_f32 v[40:41], v[38:39], v[40:41], s[26:27] op_sel_hi:[1,1,0]
	v_exp_f32_e32 v42, v42
	v_exp_f32_e32 v43, v43
	v_fma_f32 v44, |v30|, s20, 1.0
	v_fma_f32 v45, |v31|, s20, 1.0
	v_pk_fma_f32 v[40:41], v[38:39], v[40:41], s[36:37] op_sel_hi:[1,1,0]
	v_rcp_f32_e32 v44, v44
	v_rcp_f32_e32 v45, v45
	v_pk_fma_f32 v[40:41], v[38:39], v[40:41], s[38:39] op_sel_hi:[1,1,0]
	v_pk_mul_f32 v[38:39], v[38:39], v[40:41]
	v_pk_mul_f32 v[40:41], v[30:31], v[30:31]
	v_pk_mul_f32 v[38:39], v[42:43], v[38:39]
	v_pk_mul_f32 v[40:41], v[40:41], s[40:41] op_sel_hi:[1,0]
	v_pk_mul_f32 v[42:43], v[28:29], v[38:39]
	v_max_f32_e32 v48, 0, v28
	v_max_f32_e32 v49, 0, v29
	v_pk_fma_f32 v[38:39], v[44:45], s[22:23], v[36:37] op_sel_hi:[1,0,0]
	v_exp_f32_e32 v40, v40
	v_pk_fma_f32 v[38:39], v[44:45], v[38:39], s[26:27] op_sel_hi:[1,1,0]
	v_exp_f32_e32 v41, v41
	v_pk_fma_f32 v[38:39], v[44:45], v[38:39], s[36:37] op_sel_hi:[1,1,0]
	v_pk_fma_f32 v[38:39], v[44:45], v[38:39], s[38:39] op_sel_hi:[1,1,0]
	v_fma_f32 v46, |v26|, s20, 1.0
	v_fma_f32 v47, |v27|, s20, 1.0
	v_pk_mul_f32 v[38:39], v[44:45], v[38:39]
	v_fma_f32 v44, |v24|, s20, 1.0
	v_fma_f32 v45, |v25|, s20, 1.0
	v_pk_mul_f32 v[38:39], v[40:41], v[38:39]
	v_rcp_f32_e32 v44, v44
	v_rcp_f32_e32 v45, v45
	v_pk_mul_f32 v[40:41], v[24:25], v[24:25]
	v_pk_mul_f32 v[50:51], v[30:31], v[38:39]
	v_max_f32_e32 v52, 0, v30
	v_max_f32_e32 v53, 0, v31
	v_pk_fma_f32 v[38:39], v[44:45], s[22:23], v[36:37] op_sel_hi:[1,0,0]
	v_pk_mul_f32 v[40:41], v[40:41], s[40:41] op_sel_hi:[1,0]
	v_pk_fma_f32 v[38:39], v[44:45], v[38:39], s[26:27] op_sel_hi:[1,1,0]
	v_exp_f32_e32 v40, v40
	v_exp_f32_e32 v41, v41
	v_pk_fma_f32 v[38:39], v[44:45], v[38:39], s[36:37] op_sel_hi:[1,1,0]
	v_rcp_f32_e32 v46, v46
	v_pk_fma_f32 v[38:39], v[44:45], v[38:39], s[38:39] op_sel_hi:[1,1,0]
	v_rcp_f32_e32 v47, v47
	v_pk_mul_f32 v[38:39], v[44:45], v[38:39]
	v_pk_mul_f32 v[38:39], v[40:41], v[38:39]
	v_pk_mul_f32 v[44:45], v[26:27], v[26:27]
	v_pk_mul_f32 v[40:41], v[24:25], v[38:39]
	v_max_f32_e32 v38, 0, v24
	v_max_f32_e32 v39, 0, v25
	v_pk_mul_f32 v[54:55], v[20:21], v[20:21]
	v_sub_f32_e64 v25, v39, |v41|
	v_pk_mul_f32 v[54:55], v[54:55], s[40:41] op_sel_hi:[1,0]
	v_sub_f32_e64 v24, v38, |v40|
	v_pk_fma_f32 v[38:39], v[46:47], s[22:23], v[36:37] op_sel_hi:[1,0,0]
	v_pk_mul_f32 v[40:41], v[44:45], s[40:41] op_sel_hi:[1,0]
	v_pk_fma_f32 v[38:39], v[46:47], v[38:39], s[26:27] op_sel_hi:[1,1,0]
	v_exp_f32_e32 v40, v40
	v_exp_f32_e32 v41, v41
	v_pk_fma_f32 v[38:39], v[46:47], v[38:39], s[36:37] op_sel_hi:[1,1,0]
	v_pk_fma_f32 v[38:39], v[46:47], v[38:39], s[38:39] op_sel_hi:[1,1,0]
	v_exp_f32_e32 v54, v54
	v_pk_mul_f32 v[38:39], v[46:47], v[38:39]
	v_exp_f32_e32 v55, v55
	v_pk_mul_f32 v[38:39], v[40:41], v[38:39]
	v_fma_f32 v56, |v22|, s20, 1.0
	v_fma_f32 v57, |v23|, s20, 1.0
	v_pk_mul_f32 v[44:45], v[26:27], v[38:39]
	v_max_f32_e32 v46, 0, v26
	v_max_f32_e32 v47, 0, v27
	v_fma_f32 v38, |v20|, s20, 1.0
	v_fma_f32 v39, |v21|, s20, 1.0
	v_rcp_f32_e32 v56, v56
	v_rcp_f32_e32 v38, v38
	v_rcp_f32_e32 v39, v39
	v_rcp_f32_e32 v57, v57
	v_add_u32_e32 v32, 0xa0, v148
	v_pk_fma_f32 v[40:41], v[38:39], s[22:23], v[36:37] op_sel_hi:[1,0,0]
	v_sub_f32_e64 v26, v46, |v44|
	v_pk_fma_f32 v[40:41], v[38:39], v[40:41], s[26:27] op_sel_hi:[1,1,0]
	v_pk_fma_f32 v[40:41], v[38:39], v[40:41], s[36:37] op_sel_hi:[1,1,0]
	v_ashrrev_i32_e32 v33, 31, v32
	v_pk_fma_f32 v[40:41], v[38:39], v[40:41], s[38:39] op_sel_hi:[1,1,0]
	s_waitcnt lgkmcnt(0)
	v_lshl_add_u64 v[34:35], s[50:51], 0, v[32:33]
	v_pk_mul_f32 v[38:39], v[38:39], v[40:41]
	v_pk_mul_f32 v[40:41], v[22:23], v[22:23]
	v_pk_mul_f32 v[38:39], v[54:55], v[38:39]
	v_pk_mul_f32 v[40:41], v[40:41], s[40:41] op_sel_hi:[1,0]
	v_pk_mul_f32 v[54:55], v[20:21], v[38:39]
	v_max_f32_e32 v58, 0, v20
	v_max_f32_e32 v59, 0, v21
	v_pk_fma_f32 v[38:39], v[56:57], s[22:23], v[36:37] op_sel_hi:[1,0,0]
	v_exp_f32_e32 v40, v40
	v_pk_fma_f32 v[38:39], v[56:57], v[38:39], s[26:27] op_sel_hi:[1,1,0]
	v_exp_f32_e32 v41, v41
	v_pk_fma_f32 v[38:39], v[56:57], v[38:39], s[36:37] op_sel_hi:[1,1,0]
	v_lshlrev_b64 v[34:35], 8, v[34:35]
	v_pk_fma_f32 v[38:39], v[56:57], v[38:39], s[38:39] op_sel_hi:[1,1,0]
	v_lshl_add_u64 v[34:35], v[138:139], 0, v[34:35]
	v_pk_mul_f32 v[38:39], v[56:57], v[38:39]
	v_cvt_pk_bf16_f32 v46, v24, v25
	v_pk_mul_f32 v[38:39], v[40:41], v[38:39]
	s_nop 0
	v_pk_mul_f32 v[40:41], v[22:23], v[38:39]
	v_max_f32_e32 v56, 0, v22
	v_max_f32_e32 v57, 0, v23
	v_fma_f32 v38, |v16|, s20, 1.0
	v_fma_f32 v39, |v17|, s20, 1.0
	s_nop 0
	v_rcp_f32_e32 v60, v38
	v_rcp_f32_e32 v61, v39
	v_sub_f32_e64 v39, v56, |v40|
	v_sub_f32_e64 v23, v57, |v41|
	v_pk_mul_f32 v[56:57], v[16:17], v[16:17]
	v_pk_fma_f32 v[40:41], v[60:61], s[22:23], v[36:37] op_sel_hi:[1,0,0]
	v_pk_mul_f32 v[56:57], v[56:57], s[40:41] op_sel_hi:[1,0]
	v_pk_fma_f32 v[40:41], v[60:61], v[40:41], s[26:27] op_sel_hi:[1,1,0]
	v_exp_f32_e32 v56, v56
	v_exp_f32_e32 v57, v57
	v_pk_fma_f32 v[40:41], v[60:61], v[40:41], s[36:37] op_sel_hi:[1,1,0]
	v_pk_fma_f32 v[40:41], v[60:61], v[40:41], s[38:39] op_sel_hi:[1,1,0]
	s_nop 0
	v_pk_mul_f32 v[40:41], v[60:61], v[40:41]
	v_pk_mul_f32 v[60:61], v[18:19], v[18:19]
	v_pk_mul_f32 v[40:41], v[56:57], v[40:41]
	s_nop 0
	v_pk_mul_f32 v[56:57], v[16:17], v[40:41]
	v_max_f32_e32 v62, 0, v16
	v_max_f32_e32 v63, 0, v17
	v_sub_f32_e64 v40, v48, |v42|
	v_sub_f32_e64 v41, v58, |v54|
	v_sub_f32_e64 v42, v49, |v43|
	v_fma_f32 v48, |v18|, s20, 1.0
	v_fma_f32 v49, |v19|, s20, 1.0
	v_sub_f32_e64 v28, v52, |v50|
	v_rcp_f32_e32 v48, v48
	v_rcp_f32_e32 v49, v49
	v_sub_f32_e64 v29, v59, |v55|
	v_cvt_pk_bf16_f32 v44, v40, v42
	v_pk_fma_f32 v[36:37], v[48:49], s[22:23], v[36:37] op_sel_hi:[1,0,0]
	v_sub_f32_e64 v30, v53, |v51|
	v_pk_fma_f32 v[36:37], v[48:49], v[36:37], s[26:27] op_sel_hi:[1,1,0]
	v_sub_f32_e64 v20, v62, |v56|
	v_pk_fma_f32 v[36:37], v[48:49], v[36:37], s[36:37] op_sel_hi:[1,1,0]
	v_sub_f32_e64 v21, v47, |v45|
	v_cvt_pk_bf16_f32 v45, v28, v30
	v_cvt_pk_bf16_f32 v47, v26, v21
	global_store_dwordx4 v[34:35], v[44:47], off
	v_pk_fma_f32 v[36:37], v[48:49], v[36:37], s[38:39] op_sel_hi:[1,1,0]
	s_nop 0
	v_pk_mul_f32 v[44:45], v[60:61], s[40:41] op_sel_hi:[1,0]
	v_pk_mul_f32 v[36:37], v[48:49], v[36:37]
	v_exp_f32_e32 v44, v44
	v_exp_f32_e32 v45, v45
	v_sub_f32_e64 v16, v63, |v57|
	v_cvt_pk_bf16_f32 v46, v20, v16
	v_pk_mul_f32 v[36:37], v[44:45], v[36:37]
	s_nop 0
	v_pk_mul_f32 v[44:45], v[18:19], v[36:37]
	v_max_f32_e32 v36, 0, v18
	v_max_f32_e32 v37, 0, v19
	v_sub_f32_e64 v19, v37, |v45|
	v_cvt_pk_bf16_f32 v45, v39, v23
	v_sub_f32_e64 v18, v36, |v44|
	v_add_co_u32_e32 v34, vcc, 0x820000, v34
	v_cvt_pk_bf16_f32 v44, v41, v29
	s_nop 0
	v_addc_co_u32_e32 v35, vcc, 0, v35, vcc
	v_cvt_pk_bf16_f32 v47, v18, v19
	s_and_b64 vcc, exec, s[6:7]
	global_store_dwordx4 v[34:35], v[44:47], off
	s_cbranch_vccnz .LBB0_201
	v_mov_b32_e32 v43, v41
	v_mov_b32_e32 v17, v21
	v_mov_b32_e32 v31, v29
	v_pk_add_f32 v[34:35], v[20:21], v[16:17]
	v_pk_mul_f32 v[36:37], v[20:21], v[16:17]
	v_mov_b32_e32 v44, v42
	v_pk_add_f32 v[48:49], v[40:41], v[42:43]
	v_pk_mul_f32 v[42:43], v[40:41], v[42:43]
	v_mov_b32_e32 v35, v37
	v_mov_b32_e32 v37, v28
	v_mov_b32_e32 v45, v30
	v_mov_b32_e32 v49, v43
	v_pk_add_f32 v[42:43], v[28:29], v[30:31]
	v_pk_mul_f32 v[30:31], v[28:29], v[30:31]
	v_and_b32_e32 v28, 64, v166
	v_xor_b32_e32 v27, 16, v166
	v_add_u32_e32 v28, 64, v28
	v_mov_b32_e32 v36, v40
	v_pk_mul_f32 v[44:45], v[44:45], v[44:45]
	v_mul_f32_e32 v22, v24, v24
	v_cmp_lt_i32_e32 vcc, v27, v28
	v_pk_fma_f32 v[36:37], v[36:37], v[36:37], v[44:45]
	v_pk_fma_f32 v[44:45], v[24:25], v[24:25], v[22:23] op_sel_hi:[1,1,0]
	v_mul_f32_e32 v22, v18, v18
	v_mov_b32_e32 v43, v31
	v_mul_f32_e32 v31, v39, v39
	v_mul_f32_e32 v51, v23, v23
	v_pk_mul_f32 v[52:53], v[20:21], v[20:21]
	v_pk_mul_f32 v[16:17], v[16:17], v[16:17]
	v_cndmask_b32_e32 v27, v166, v27, vcc
	v_mov_b32_e32 v30, v24
	v_mov_b32_e32 v50, v25
	v_pk_fma_f32 v[46:47], v[18:19], v[18:19], v[22:23] op_sel_hi:[1,1,0]
	v_mov_b32_e32 v38, v41
	v_mov_b32_e32 v22, v29
	v_lshlrev_b32_e32 v29, 2, v27
	v_mov_b32_e32 v27, v52
	v_pk_mov_b32 v[16:17], v[20:21], v[16:17] op_sel:[1,0]
	v_pk_add_f32 v[20:21], v[48:49], v[42:43]
	v_pk_add_f32 v[24:25], v[30:31], v[50:51]
	v_pk_add_f32 v[22:23], v[38:39], v[22:23]
	v_pk_add_f32 v[16:17], v[26:27], v[16:17]
	v_pk_add_f32 v[20:21], v[20:21], v[24:25]
	v_mul_f32_e32 v33, v26, v26
	v_pk_add_f32 v[36:37], v[36:37], v[36:37] op_sel_hi:[0,1]
	v_pk_add_f32 v[16:17], v[20:21], v[16:17]
	v_pk_add_f32 v[20:21], v[22:23], v[22:23] op_sel:[0,1] op_sel_hi:[1,0]
	v_mov_b32_e32 v36, v18
	v_mov_b32_e32 v44, v19
	v_mov_b32_e32 v21, v33
	v_mov_b32_e32 v137, v47
	v_pk_add_f32 v[18:19], v[36:37], v[44:45]
	v_pk_add_f32 v[20:21], v[20:21], v[34:35]
	v_pk_add_f32 v[16:17], v[16:17], v[136:137]
	v_pk_add_f32 v[18:19], v[20:21], v[18:19]
	v_xor_b32_e32 v20, 32, v166
	v_pk_add_f32 v[16:17], v[18:19], v[16:17]
	ds_bpermute_b32 v18, v29, v16
	ds_bpermute_b32 v19, v29, v17
	v_cmp_lt_i32_e32 vcc, v20, v28
	s_waitcnt lgkmcnt(0)
	v_pk_add_f32 v[16:17], v[16:17], v[18:19]
	v_cndmask_b32_e32 v20, v166, v20, vcc
	v_lshlrev_b32_e32 v20, 2, v20
	ds_bpermute_b32 v18, v20, v16
	ds_bpermute_b32 v19, v20, v17
	s_and_saveexec_b64 s[52:53], s[2:3]
	s_cbranch_execz .LBB0_200
	s_lshl_b32 s29, s10, 2
	s_sub_i32 s29, s29, 48
	s_waitcnt lgkmcnt(0)
	v_pk_add_f32 v[16:17], v[16:17], v[18:19]
	v_mov_b32_e32 v18, s29
	v_mov_b32_e32 v19, v136
	v_mad_i64_i32 v[18:19], s[34:35], v32, 48, v[18:19]
	v_or_b32_e32 v18, s61, v18
	v_lshl_add_u64 v[18:19], v[18:19], 3, s[14:15]
	global_store_dwordx2 v[18:19], v[16:17], off

.LBB0_201:
	v_fma_f32 v20, |v12|, s20, 1.0
	v_fma_f32 v21, |v13|, s20, 1.0
	v_pk_mul_f32 v[26:27], v[12:13], v[12:13]
	v_rcp_f32_e32 v22, v20
	v_rcp_f32_e32 v23, v21
	v_mov_b64_e32 v[20:21], s[24:25]
	v_pk_mul_f32 v[26:27], v[26:27], s[40:41] op_sel_hi:[1,0]
	v_pk_fma_f32 v[24:25], v[22:23], s[22:23], v[20:21] op_sel_hi:[1,0,0]
	v_pk_fma_f32 v[24:25], v[22:23], v[24:25], s[26:27] op_sel_hi:[1,1,0]
	v_exp_f32_e32 v26, v26
	v_exp_f32_e32 v27, v27
	v_fma_f32 v28, |v14|, s20, 1.0
	v_fma_f32 v29, |v15|, s20, 1.0
	v_pk_fma_f32 v[24:25], v[22:23], v[24:25], s[36:37] op_sel_hi:[1,1,0]
	v_rcp_f32_e32 v28, v28
	v_rcp_f32_e32 v29, v29
	v_pk_fma_f32 v[24:25], v[22:23], v[24:25], s[38:39] op_sel_hi:[1,1,0]
	v_pk_mul_f32 v[22:23], v[22:23], v[24:25]
	v_pk_mul_f32 v[24:25], v[14:15], v[14:15]
	v_pk_mul_f32 v[22:23], v[26:27], v[22:23]
	v_pk_mul_f32 v[24:25], v[24:25], s[40:41] op_sel_hi:[1,0]
	v_pk_mul_f32 v[26:27], v[12:13], v[22:23]
	v_max_f32_e32 v32, 0, v12
	v_max_f32_e32 v33, 0, v13
	v_pk_fma_f32 v[22:23], v[28:29], s[22:23], v[20:21] op_sel_hi:[1,0,0]
	v_exp_f32_e32 v24, v24
	v_pk_fma_f32 v[22:23], v[28:29], v[22:23], s[26:27] op_sel_hi:[1,1,0]
	v_exp_f32_e32 v25, v25
	v_pk_fma_f32 v[22:23], v[28:29], v[22:23], s[36:37] op_sel_hi:[1,1,0]
	v_pk_fma_f32 v[22:23], v[28:29], v[22:23], s[38:39] op_sel_hi:[1,1,0]
	v_fma_f32 v30, |v10|, s20, 1.0
	v_fma_f32 v31, |v11|, s20, 1.0
	v_pk_mul_f32 v[22:23], v[28:29], v[22:23]
	v_fma_f32 v28, |v8|, s20, 1.0
	v_fma_f32 v29, |v9|, s20, 1.0
	v_pk_mul_f32 v[22:23], v[24:25], v[22:23]
	v_rcp_f32_e32 v28, v28
	v_rcp_f32_e32 v29, v29
	v_pk_mul_f32 v[24:25], v[8:9], v[8:9]
	v_pk_mul_f32 v[34:35], v[14:15], v[22:23]
	v_max_f32_e32 v36, 0, v14
	v_max_f32_e32 v37, 0, v15
	v_pk_fma_f32 v[22:23], v[28:29], s[22:23], v[20:21] op_sel_hi:[1,0,0]
	v_pk_mul_f32 v[24:25], v[24:25], s[40:41] op_sel_hi:[1,0]
	v_pk_fma_f32 v[22:23], v[28:29], v[22:23], s[26:27] op_sel_hi:[1,1,0]
	v_exp_f32_e32 v24, v24
	v_exp_f32_e32 v25, v25
	v_pk_fma_f32 v[22:23], v[28:29], v[22:23], s[36:37] op_sel_hi:[1,1,0]
	v_rcp_f32_e32 v30, v30
	v_pk_fma_f32 v[22:23], v[28:29], v[22:23], s[38:39] op_sel_hi:[1,1,0]
	v_rcp_f32_e32 v31, v31
	v_pk_mul_f32 v[22:23], v[28:29], v[22:23]
	v_pk_mul_f32 v[22:23], v[24:25], v[22:23]
	v_pk_mul_f32 v[28:29], v[10:11], v[10:11]
	v_pk_mul_f32 v[24:25], v[8:9], v[22:23]
	v_max_f32_e32 v22, 0, v8
	v_max_f32_e32 v23, 0, v9
	v_pk_mul_f32 v[38:39], v[4:5], v[4:5]
	v_sub_f32_e64 v9, v23, |v25|
	v_pk_mul_f32 v[38:39], v[38:39], s[40:41] op_sel_hi:[1,0]
	v_sub_f32_e64 v8, v22, |v24|
	v_pk_fma_f32 v[22:23], v[30:31], s[22:23], v[20:21] op_sel_hi:[1,0,0]
	v_pk_mul_f32 v[24:25], v[28:29], s[40:41] op_sel_hi:[1,0]
	v_pk_fma_f32 v[22:23], v[30:31], v[22:23], s[26:27] op_sel_hi:[1,1,0]
	v_exp_f32_e32 v24, v24
	v_exp_f32_e32 v25, v25
	v_pk_fma_f32 v[22:23], v[30:31], v[22:23], s[36:37] op_sel_hi:[1,1,0]
	v_pk_fma_f32 v[22:23], v[30:31], v[22:23], s[38:39] op_sel_hi:[1,1,0]
	v_exp_f32_e32 v38, v38
	v_pk_mul_f32 v[22:23], v[30:31], v[22:23]
	v_exp_f32_e32 v39, v39
	v_pk_mul_f32 v[22:23], v[24:25], v[22:23]
	v_fma_f32 v40, |v6|, s20, 1.0
	v_fma_f32 v41, |v7|, s20, 1.0
	v_pk_mul_f32 v[28:29], v[10:11], v[22:23]
	v_max_f32_e32 v30, 0, v10
	v_max_f32_e32 v31, 0, v11
	v_fma_f32 v22, |v4|, s20, 1.0
	v_fma_f32 v23, |v5|, s20, 1.0
	v_rcp_f32_e32 v40, v40
	v_rcp_f32_e32 v22, v22
	v_rcp_f32_e32 v23, v23
	v_rcp_f32_e32 v41, v41
	v_add_u32_e32 v16, 0xb0, v148
	v_pk_fma_f32 v[24:25], v[22:23], s[22:23], v[20:21] op_sel_hi:[1,0,0]
	v_sub_f32_e64 v10, v30, |v28|
	v_pk_fma_f32 v[24:25], v[22:23], v[24:25], s[26:27] op_sel_hi:[1,1,0]
	v_pk_fma_f32 v[24:25], v[22:23], v[24:25], s[36:37] op_sel_hi:[1,1,0]
	v_ashrrev_i32_e32 v17, 31, v16
	v_pk_fma_f32 v[24:25], v[22:23], v[24:25], s[38:39] op_sel_hi:[1,1,0]
	s_waitcnt lgkmcnt(0)
	v_lshl_add_u64 v[18:19], s[50:51], 0, v[16:17]
	v_pk_mul_f32 v[22:23], v[22:23], v[24:25]
	v_pk_mul_f32 v[24:25], v[6:7], v[6:7]
	v_pk_mul_f32 v[22:23], v[38:39], v[22:23]
	v_pk_mul_f32 v[24:25], v[24:25], s[40:41] op_sel_hi:[1,0]
	v_pk_mul_f32 v[38:39], v[4:5], v[22:23]
	v_max_f32_e32 v42, 0, v4
	v_max_f32_e32 v43, 0, v5
	v_pk_fma_f32 v[22:23], v[40:41], s[22:23], v[20:21] op_sel_hi:[1,0,0]
	v_exp_f32_e32 v24, v24
	v_pk_fma_f32 v[22:23], v[40:41], v[22:23], s[26:27] op_sel_hi:[1,1,0]
	v_exp_f32_e32 v25, v25
	v_pk_fma_f32 v[22:23], v[40:41], v[22:23], s[36:37] op_sel_hi:[1,1,0]
	v_lshlrev_b64 v[18:19], 8, v[18:19]
	v_pk_fma_f32 v[22:23], v[40:41], v[22:23], s[38:39] op_sel_hi:[1,1,0]
	v_lshl_add_u64 v[18:19], v[138:139], 0, v[18:19]
	v_pk_mul_f32 v[22:23], v[40:41], v[22:23]
	v_cvt_pk_bf16_f32 v30, v8, v9
	v_pk_mul_f32 v[22:23], v[24:25], v[22:23]
	s_nop 0
	v_pk_mul_f32 v[24:25], v[6:7], v[22:23]
	v_max_f32_e32 v40, 0, v6
	v_max_f32_e32 v41, 0, v7
	v_fma_f32 v22, |v0|, s20, 1.0
	v_fma_f32 v23, |v1|, s20, 1.0
	s_nop 0
	v_rcp_f32_e32 v44, v22
	v_rcp_f32_e32 v45, v23
	v_sub_f32_e64 v23, v40, |v24|
	v_sub_f32_e64 v7, v41, |v25|
	v_pk_mul_f32 v[40:41], v[0:1], v[0:1]
	v_pk_fma_f32 v[24:25], v[44:45], s[22:23], v[20:21] op_sel_hi:[1,0,0]
	v_pk_mul_f32 v[40:41], v[40:41], s[40:41] op_sel_hi:[1,0]
	v_pk_fma_f32 v[24:25], v[44:45], v[24:25], s[26:27] op_sel_hi:[1,1,0]
	v_exp_f32_e32 v40, v40
	v_exp_f32_e32 v41, v41
	v_pk_fma_f32 v[24:25], v[44:45], v[24:25], s[36:37] op_sel_hi:[1,1,0]
	v_pk_fma_f32 v[24:25], v[44:45], v[24:25], s[38:39] op_sel_hi:[1,1,0]
	s_nop 0
	v_pk_mul_f32 v[24:25], v[44:45], v[24:25]
	v_pk_mul_f32 v[44:45], v[2:3], v[2:3]
	v_pk_mul_f32 v[24:25], v[40:41], v[24:25]
	s_nop 0
	v_pk_mul_f32 v[40:41], v[0:1], v[24:25]
	v_max_f32_e32 v46, 0, v0
	v_max_f32_e32 v47, 0, v1
	v_sub_f32_e64 v24, v32, |v26|
	v_sub_f32_e64 v25, v42, |v38|
	v_sub_f32_e64 v26, v33, |v27|
	v_fma_f32 v32, |v2|, s20, 1.0
	v_fma_f32 v33, |v3|, s20, 1.0
	v_sub_f32_e64 v12, v36, |v34|
	v_rcp_f32_e32 v32, v32
	v_rcp_f32_e32 v33, v33
	v_sub_f32_e64 v13, v43, |v39|
	v_cvt_pk_bf16_f32 v28, v24, v26
	v_pk_fma_f32 v[20:21], v[32:33], s[22:23], v[20:21] op_sel_hi:[1,0,0]
	v_sub_f32_e64 v14, v37, |v35|
	v_pk_fma_f32 v[20:21], v[32:33], v[20:21], s[26:27] op_sel_hi:[1,1,0]
	v_sub_f32_e64 v4, v46, |v40|
	v_pk_fma_f32 v[20:21], v[32:33], v[20:21], s[36:37] op_sel_hi:[1,1,0]
	v_sub_f32_e64 v5, v31, |v29|
	v_cvt_pk_bf16_f32 v29, v12, v14
	v_cvt_pk_bf16_f32 v31, v10, v5
	global_store_dwordx4 v[18:19], v[28:31], off
	v_pk_fma_f32 v[20:21], v[32:33], v[20:21], s[38:39] op_sel_hi:[1,1,0]
	s_nop 0
	v_pk_mul_f32 v[28:29], v[44:45], s[40:41] op_sel_hi:[1,0]
	v_pk_mul_f32 v[20:21], v[32:33], v[20:21]
	v_exp_f32_e32 v28, v28
	v_exp_f32_e32 v29, v29
	v_sub_f32_e64 v0, v47, |v41|
	v_cvt_pk_bf16_f32 v30, v4, v0
	v_pk_mul_f32 v[20:21], v[28:29], v[20:21]
	s_nop 0
	v_pk_mul_f32 v[28:29], v[2:3], v[20:21]
	v_max_f32_e32 v20, 0, v2
	v_max_f32_e32 v21, 0, v3
	v_sub_f32_e64 v3, v21, |v29|
	v_cvt_pk_bf16_f32 v29, v23, v7
	v_sub_f32_e64 v2, v20, |v28|
	v_add_co_u32_e32 v18, vcc, 0x820000, v18
	v_cvt_pk_bf16_f32 v28, v25, v13
	s_nop 0
	v_addc_co_u32_e32 v19, vcc, 0, v19, vcc
	v_cvt_pk_bf16_f32 v31, v2, v3
	s_and_b64 vcc, exec, s[6:7]
	global_store_dwordx4 v[18:19], v[28:31], off
	s_cbranch_vccnz .LBB0_205
	v_mov_b32_e32 v27, v25
	v_mov_b32_e32 v1, v5
	v_mov_b32_e32 v15, v13
	v_pk_add_f32 v[18:19], v[4:5], v[0:1]
	v_pk_mul_f32 v[20:21], v[4:5], v[0:1]
	v_mov_b32_e32 v28, v26
	v_pk_add_f32 v[32:33], v[24:25], v[26:27]
	v_pk_mul_f32 v[26:27], v[24:25], v[26:27]
	v_mov_b32_e32 v19, v21
	v_mov_b32_e32 v21, v12
	v_mov_b32_e32 v29, v14
	v_mov_b32_e32 v33, v27
	v_pk_add_f32 v[26:27], v[12:13], v[14:15]
	v_pk_mul_f32 v[14:15], v[12:13], v[14:15]
	v_and_b32_e32 v12, 64, v166
	v_xor_b32_e32 v11, 16, v166
	v_add_u32_e32 v12, 64, v12
	v_mov_b32_e32 v20, v24
	v_pk_mul_f32 v[28:29], v[28:29], v[28:29]
	v_mul_f32_e32 v6, v8, v8
	v_cmp_lt_i32_e32 vcc, v11, v12
	v_pk_fma_f32 v[20:21], v[20:21], v[20:21], v[28:29]
	v_pk_fma_f32 v[28:29], v[8:9], v[8:9], v[6:7] op_sel_hi:[1,1,0]
	v_mul_f32_e32 v6, v2, v2
	v_mov_b32_e32 v27, v15
	v_mul_f32_e32 v15, v23, v23
	v_mul_f32_e32 v35, v7, v7
	v_pk_mul_f32 v[36:37], v[4:5], v[4:5]
	v_pk_mul_f32 v[0:1], v[0:1], v[0:1]
	v_cndmask_b32_e32 v11, v166, v11, vcc
	v_mov_b32_e32 v14, v8
	v_mov_b32_e32 v34, v9
	v_pk_fma_f32 v[30:31], v[2:3], v[2:3], v[6:7] op_sel_hi:[1,1,0]
	v_mov_b32_e32 v22, v25
	v_mov_b32_e32 v6, v13
	v_lshlrev_b32_e32 v13, 2, v11
	v_mov_b32_e32 v11, v36
	v_pk_mov_b32 v[0:1], v[4:5], v[0:1] op_sel:[1,0]
	v_pk_add_f32 v[4:5], v[32:33], v[26:27]
	v_pk_add_f32 v[8:9], v[14:15], v[34:35]
	v_pk_add_f32 v[6:7], v[22:23], v[6:7]
	v_pk_add_f32 v[0:1], v[10:11], v[0:1]
	v_pk_add_f32 v[4:5], v[4:5], v[8:9]
	v_mul_f32_e32 v17, v10, v10
	v_pk_add_f32 v[20:21], v[20:21], v[20:21] op_sel_hi:[0,1]
	v_pk_add_f32 v[0:1], v[4:5], v[0:1]
	v_pk_add_f32 v[4:5], v[6:7], v[6:7] op_sel:[0,1] op_sel_hi:[1,0]
	v_mov_b32_e32 v20, v2
	v_mov_b32_e32 v28, v3
	v_mov_b32_e32 v5, v17
	v_mov_b32_e32 v137, v31
	v_pk_add_f32 v[2:3], v[20:21], v[28:29]
	v_pk_add_f32 v[4:5], v[4:5], v[18:19]
	v_pk_add_f32 v[0:1], v[0:1], v[136:137]
	v_pk_add_f32 v[2:3], v[4:5], v[2:3]
	v_xor_b32_e32 v4, 32, v166
	v_pk_add_f32 v[0:1], v[2:3], v[0:1]
	ds_bpermute_b32 v2, v13, v0
	ds_bpermute_b32 v3, v13, v1
	v_cmp_lt_i32_e32 vcc, v4, v12
	s_waitcnt lgkmcnt(0)
	v_pk_add_f32 v[0:1], v[0:1], v[2:3]
	v_cndmask_b32_e32 v4, v166, v4, vcc
	v_lshlrev_b32_e32 v4, 2, v4
	ds_bpermute_b32 v2, v4, v0
	ds_bpermute_b32 v3, v4, v1
	s_and_saveexec_b64 s[6:7], s[2:3]
	s_cbranch_execz .LBB0_204
	s_lshl_b32 s10, s10, 2
	s_sub_i32 s10, s10, 48
	s_waitcnt lgkmcnt(0)
	v_pk_add_f32 v[0:1], v[0:1], v[2:3]
	v_mov_b32_e32 v2, s10
	v_mov_b32_e32 v3, v136
	v_mad_i64_i32 v[2:3], s[34:35], v16, 48, v[2:3]
	v_or_b32_e32 v2, s61, v2
	v_lshl_add_u64 v[2:3], v[2:3], 3, s[14:15]
	global_store_dwordx2 v[2:3], v[0:1], off
